# R2/R3 fast bodies: when both rows of an iteration use the same modulation rows (same batch, same kind) gate/shift/scale are loaded once and shared
# speedup vs baseline: 1.0124x; 1.0025x over previous
; __device__ __forceinline__ float bflo(unsigned w) { return __uint_as_float(w << 16); }
; __device__ __forceinline__ float bfhi(unsigned w) { return __uint_as_float(w & 0xffff0000u); }
; __device__ __forceinline__ void row_pass(const RowPass& R, int gw, int ngw, int lane) {
;     ...
;     for (int row0 = gw; row0 < M; row0 += NR * ngw) {
;         f32x4 v[NR][4]; u32x2 yw[NR][4]; bool act[NR]; float* xrow[NR]; int bbs[NR];
; #pragma unroll
;         for (int k = 0; k < NR; ++k) {
;             const int row = row0 + k * ngw;
;             const int rowc = row < M ? row : row0;
;             const int b = rowc / RPB, i = rowc - b * RPB; const bool isctx = i < CTXL;
;             act[k] = (row < M) && !(isctx && R.skip_ctx);
;             bbs[k] = isctx ? 8 : b;
;             xrow[k] = isctx ? R.xc + ((size_t)b * CTXL + i) * DM : R.out + ((size_t)b * SEQ + (i - CTXL)) * DM;
;             const float* src = R.init ? (isctx ? R.ctx_in + ((size_t)b * CTXL + i) * DM : R.x_in + ((size_t)b * SEQ + (i - CTXL)) * DM) : xrow[k];
;             if (act[k]) {
; #pragma unroll
;                 for (int j = 0; j < 4; ++j) v[k][j] = __builtin_nontemporal_load((const f32x4*)(src + lane * 4 + 256 * j));
;                 if (R.update) { const bf16* yr = R.Y + (size_t)rowc * DM;
; #pragma unroll
;                     for (int j = 0; j < 4; ++j) yw[k][j] = __builtin_nontemporal_load((const u32x2*)(yr + lane * 4 + 256 * j)); }
;             }
;         }
; #pragma unroll
;         for (int k = 0; k < NR; ++k) {
;             if (!act[k]) continue;
;             const int row = row0 + k * ngw, bb = bbs[k];
;             if (R.update) {
;                 f32x4 y[4]; float ss = 0.f;
; #pragma unroll
;                 for (int j = 0; j < 4; ++j) { const u32x2 w = yw[k][j]; y[j] = (f32x4){bflo(w.x), bfhi(w.x), bflo(w.y), bfhi(w.y)};
;                     ss += (y[j][0] * y[j][0] + y[j][1] * y[j][1]) + (y[j][2] * y[j][2] + y[j][3] * y[j][3]); }
;                 const float rstd = __builtin_amdgcn_rsqf(wave_sum(ss) * (1.0f / DM) + EPS);
;                 const float* gate = R.mod + ((size_t)(R.lg * 9 + bb) * NMOD + R.gi) * DM;
; #pragma unroll
;                 for (int j = 0; j < 4; ++j) { const f32x4 g = *(const f32x4*)(gate + lane * 4 + 256 * j), gp = *(const f32x4*)(R.gpost + lane * 4 + 256 * j);
;                     v[k][j] = v[k][j] + g * (y[j] * rstd * gp); }
.LBB0_132:
	s_mul_hi_i32 s6, s13, 0x78787879
	s_lshr_b32 s7, s6, 31
	s_ashr_i32 s6, s6, 11
	s_add_i32 s6, s6, s7
	s_mul_i32 s7, s6, 0xffffef00
	s_add_i32 s7, s13, s7
	s_cmpk_gt_i32 s7, 0xff
	s_cselect_b64 s[50:51], -1, 0
	s_add_i32 s8, s44, s13
	s_cmp_lt_i32 s8, 0x8800
	s_cbranch_scc0 .Lr2_slow
	s_mul_hi_i32 s9, s8, 0x78787879
	s_lshr_b32 s25, s9, 31
	s_ashr_i32 s9, s9, 11
	s_add_i32 s9, s9, s25
	s_mul_i32 s25, s9, 0xffffef00
	s_add_i32 s25, s8, s25
	s_cmpk_gt_i32 s25, 0xff
	s_cselect_b64 s[52:53], -1, 0
	s_and_b64 s[46:47], s[50:51], s[52:53]
	s_or_b64 s[46:47], s[46:47], s[62:63]
	s_cmp_lg_u64 s[46:47], 0
	s_cbranch_scc0 .Lr2_slow
	v_lshlrev_b32_e32 v160, 2, v36
	s_cmp_lg_u32 s6, s9
	s_cbranch_scc1 .Lr2_slow_diff
	s_cmp_eq_u32 s50, s52
	s_cbranch_scc1 .Lr2_slow_same
.Lr2_slow_diff:
	s_add_i32 s72, s7, 0xffffff00
	s_cmp_lg_u64 s[50:51], 0
	s_cselect_b32 s27, s4, s49
	s_cselect_b32 s32, s5, s55
	s_cselect_b32 s37, 24, 20
	s_cselect_b32 s72, s72, s7
	s_cselect_b32 s85, s6, 8
	s_mov_b32 s40, s6
	s_mov_b32 s41, 0
	s_lshl_b64 s[40:41], s[40:41], s37
	s_add_u32 s40, s27, s40
	s_addc_u32 s41, s32, s41
	s_lshl_b32 s72, s72, 12
	s_add_u32 s40, s40, s72
	s_addc_u32 s41, s41, 0
	s_add_i32 s27, s85, s3
	s_mul_hi_i32 s32, s27, 0x6000
	s_mulk_i32 s27, 0x6000
	s_add_u32 s66, s34, s27
	s_addc_u32 s67, s35, s32
	s_add_u32 s66, s66, 0x2000
	s_addc_u32 s67, s67, 0
	s_add_i32 s27, s85, s3
	s_mul_hi_i32 s32, s27, 0x6000
	s_mulk_i32 s27, 0x6000
	s_add_u32 s38, s34, s27
	s_addc_u32 s39, s35, s32
	s_add_u32 s38, s38, 0x3000
	s_addc_u32 s39, s39, 0
	s_add_u32 s46, s38, 0x1000
	s_addc_u32 s47, s39, 0
	global_load_dwordx4 v[12:15], v160, s[40:41] nt
	global_load_dwordx4 v[8:11], v160, s[40:41] offset:1024 nt
	global_load_dwordx4 v[4:7], v160, s[40:41] offset:2048 nt
	global_load_dwordx4 v[0:3], v160, s[40:41] offset:3072 nt
	global_load_dwordx2 v[54:55], v[46:47], off offset:-1536 nt
	global_load_dwordx2 v[52:53], v[46:47], off offset:-1024 nt
	global_load_dwordx2 v[50:51], v[46:47], off offset:-512 nt
	global_load_dwordx2 v[48:49], v[46:47], off nt
	global_load_dwordx4 v[64:67], v160, s[66:67]
	global_load_dwordx4 v[68:71], v160, s[66:67] offset:1024
	global_load_dwordx4 v[72:75], v160, s[66:67] offset:2048
	global_load_dwordx4 v[76:79], v160, s[66:67] offset:3072
	s_mov_b32 s6, s8
	s_ashr_i32 s7, s8, 31
	s_lshl_b64 s[6:7], s[6:7], 11
	v_lshl_add_u64 v[250:251], v[38:39], 0, s[6:7]
	v_lshl_add_u64 v[252:253], v[40:41], 0, s[6:7]
	s_mov_b64 s[6:7], s[52:53]
	s_add_i32 s72, s25, 0xffffff00
	s_cmp_lg_u64 s[6:7], 0
	s_cselect_b32 s27, s4, s49
	s_cselect_b32 s32, s5, s55
	s_cselect_b32 s37, 24, 20
	s_cselect_b32 s72, s72, s25
	s_cselect_b32 s85, s9, 8
	s_mov_b32 s64, s9
	s_mov_b32 s65, 0
	s_lshl_b64 s[64:65], s[64:65], s37
	s_add_u32 s64, s27, s64
	s_addc_u32 s65, s32, s65
	s_lshl_b32 s72, s72, 12
	s_add_u32 s64, s64, s72
	s_addc_u32 s65, s65, 0
	s_add_i32 s27, s85, s3
	s_mul_hi_i32 s32, s27, 0x6000
	s_mulk_i32 s27, 0x6000
	s_add_u32 s10, s34, s27
	s_addc_u32 s11, s35, s32
	s_add_u32 s10, s10, 0x2000
	s_addc_u32 s11, s11, 0
	s_add_i32 s27, s85, s3
	s_mul_hi_i32 s32, s27, 0x6000
	s_mulk_i32 s27, 0x6000
	s_add_u32 s50, s34, s27
	s_addc_u32 s51, s35, s32
	s_add_u32 s50, s50, 0x3000
	s_addc_u32 s51, s51, 0
	s_add_u32 s52, s50, 0x1000
	s_addc_u32 s53, s51, 0
	global_load_dwordx4 v[16:19], v160, s[64:65] nt
	global_load_dwordx4 v[20:23], v160, s[64:65] offset:1024 nt
	global_load_dwordx4 v[24:27], v160, s[64:65] offset:2048 nt
	global_load_dwordx4 v[28:31], v160, s[64:65] offset:3072 nt
	global_load_dwordx2 v[62:63], v[250:251], off nt
	global_load_dwordx2 v[60:61], v[250:251], off offset:512 nt
	global_load_dwordx2 v[58:59], v[250:251], off offset:1024 nt
	global_load_dwordx2 v[56:57], v[250:251], off offset:1536 nt
	global_load_dwordx4 v[80:83], v160, s[38:39]
	global_load_dwordx4 v[84:87], v160, s[38:39] offset:1024
	global_load_dwordx4 v[88:91], v160, s[38:39] offset:2048
	global_load_dwordx4 v[92:95], v160, s[38:39] offset:3072
	global_load_dwordx4 v[172:175], v160, s[46:47]
	global_load_dwordx4 v[176:179], v160, s[46:47] offset:1024
	global_load_dwordx4 v[180:183], v160, s[46:47] offset:2048
	global_load_dwordx4 v[184:187], v160, s[46:47] offset:3072
	global_load_dwordx4 v[188:191], v160, s[10:11]
	global_load_dwordx4 v[192:195], v160, s[10:11] offset:1024
	global_load_dwordx4 v[196:199], v160, s[10:11] offset:2048
	global_load_dwordx4 v[96:99], v160, s[10:11] offset:3072
	s_waitcnt vmcnt(24)
	v_lshlrev_b32_e32 v32, 16, v54
	v_and_b32_e32 v33, 0xffff0000, v54
	v_lshlrev_b32_e32 v34, 16, v55
	v_and_b32_e32 v35, 0xffff0000, v55
	v_pk_mul_f32 v[166:167], v[32:33], v[32:33]
	v_pk_mul_f32 v[168:169], v[34:35], v[34:35]
	v_lshlrev_b32_e32 v32, 16, v52
	v_and_b32_e32 v33, 0xffff0000, v52
	v_lshlrev_b32_e32 v34, 16, v53
	v_and_b32_e32 v35, 0xffff0000, v53
	v_pk_fma_f32 v[166:167], v[32:33], v[32:33], v[166:167]
	v_pk_fma_f32 v[168:169], v[34:35], v[34:35], v[168:169]
	v_lshlrev_b32_e32 v32, 16, v50
	v_and_b32_e32 v33, 0xffff0000, v50
	v_lshlrev_b32_e32 v34, 16, v51
	v_and_b32_e32 v35, 0xffff0000, v51
	v_pk_fma_f32 v[166:167], v[32:33], v[32:33], v[166:167]
	v_pk_fma_f32 v[168:169], v[34:35], v[34:35], v[168:169]
	v_lshlrev_b32_e32 v32, 16, v48
	v_and_b32_e32 v33, 0xffff0000, v48
	v_lshlrev_b32_e32 v34, 16, v49
	v_and_b32_e32 v35, 0xffff0000, v49
	v_pk_fma_f32 v[166:167], v[32:33], v[32:33], v[166:167]
	v_pk_fma_f32 v[168:169], v[34:35], v[34:35], v[168:169]
	v_pk_add_f32 v[166:167], v[166:167], v[168:169]
	s_nop 0
	v_add_f32_e32 v164, v166, v167
	v_mov_b32_e32 v165, v164
	s_nop 1
	v_permlane32_swap_b32_e32 v165, v164
	v_add_f32_e32 v164, v164, v165
	v_mov_b32_e32 v165, v164
	s_nop 1
	v_permlane16_swap_b32_e32 v165, v164
	v_add_f32_e32 v164, v164, v165
	s_nop 1
	v_add_f32_dpp v164, v164, v164 row_ror:8 row_mask:0xf bank_mask:0xf
	s_nop 1
	v_add_f32_dpp v164, v164, v164 row_ror:4 row_mask:0xf bank_mask:0xf
	s_nop 1
	v_add_f32_dpp v164, v164, v164 row_ror:2 row_mask:0xf bank_mask:0xf
	s_nop 1
	v_add_f32_dpp v164, v164, v164 row_ror:1 row_mask:0xf bank_mask:0xf
	s_nop 0
	v_fmamk_f32 v164, v164, 0x3a800000, v200
	v_rsq_f32_e32 v164, v164
	v_lshlrev_b32_e32 v32, 16, v54
	v_and_b32_e32 v33, 0xffff0000, v54
	v_lshlrev_b32_e32 v34, 16, v55
	v_and_b32_e32 v35, 0xffff0000, v55
	v_pk_mul_f32 v[32:33], v[32:33], v[164:165] op_sel_hi:[1,0]
	v_pk_mul_f32 v[34:35], v[34:35], v[164:165] op_sel_hi:[1,0]
	v_pk_mul_f32 v[32:33], v[218:219], v[32:33]
	v_pk_mul_f32 v[34:35], v[220:221], v[34:35]
	s_waitcnt vmcnt(23)
; __device__ __forceinline__ unsigned pk2(float lo, float hi) { return pg8::cvt_pk_bf16(lo, hi); }
;     __device__ __forceinline__ void init(int N, int G, int c, int latent_only) { lat = latent_only; b.init(latent_only ? NB * SEQ : M, N, G, c); }
;     __device__ __forceinline__ void init(int c_, unsigned* cnt_) { lat.init(NB * SEQ, FF2, 1, 0); c = c_; cnt = cnt_; }
; __device__ __forceinline__ void row_pass(const RowPass& R, int gw, int ngw, int lane) {
;     ...
; #pragma unroll
;                 for (int j = 0; j < 4; ++j) { const f32x4 g = *(const f32x4*)(gate + lane * 4 + 256 * j), gp = *(const f32x4*)(R.gpost + lane * 4 + 256 * j);
;                     v[k][j] = v[k][j] + g * (y[j] * rstd * gp); }
;             }
;             if (R.init || R.update) {
; #pragma unroll
;                 for (int j = 0; j < 4; ++j) __builtin_nontemporal_store(v[k][j], (f32x4*)(xrow[k] + lane * 4 + 256 * j));
;             }
;             if (R.norm_out) {
;                 float ss = 0.f;
; #pragma unroll
;                 for (int j = 0; j < 4; ++j) ss += (v[k][j][0] * v[k][j][0] + v[k][j][1] * v[k][j][1]) + (v[k][j][2] * v[k][j][2] + v[k][j][3] * v[k][j][3]);
;                 const float rstd = __builtin_amdgcn_rsqf(wave_sum(ss) * (1.0f / DM) + EPS);
;                 const float* shift = R.mod + ((size_t)(R.ln * 9 + bb) * NMOD + R.si) * DM; const float* scale = shift + DM;
;                 bf16* hr = R.H + (size_t)row * DM;
; #pragma unroll
;                 for (int j = 0; j < 4; ++j) { const f32x4 gp = *(const f32x4*)(R.gpre + lane * 4 + 256 * j), sh = *(const f32x4*)(shift + lane * 4 + 256 * j), sc = *(const f32x4*)(scale + lane * 4 + 256 * j);
;                     const f32x4 hv = (v[k][j] * rstd * gp) * (sc + 1.0f) + sh;
;                     u32x2 w; w.x = pk2(hv[0], hv[1]); w.y = pk2(hv[2], hv[3]); *(u32x2*)(hr + lane * 4 + 256 * j) = w; }
;             }
	v_pk_fma_f32 v[12:13], v[64:65], v[32:33], v[12:13]
	v_pk_fma_f32 v[14:15], v[66:67], v[34:35], v[14:15]
	global_store_dwordx4 v160, v[12:15], s[40:41] nt
	v_lshlrev_b32_e32 v32, 16, v52
	v_and_b32_e32 v33, 0xffff0000, v52
	v_lshlrev_b32_e32 v34, 16, v53
	v_and_b32_e32 v35, 0xffff0000, v53
	v_pk_mul_f32 v[32:33], v[32:33], v[164:165] op_sel_hi:[1,0]
	v_pk_mul_f32 v[34:35], v[34:35], v[164:165] op_sel_hi:[1,0]
	v_pk_mul_f32 v[32:33], v[222:223], v[32:33]
	v_pk_mul_f32 v[34:35], v[224:225], v[34:35]
	s_waitcnt vmcnt(23)
	v_pk_fma_f32 v[8:9], v[68:69], v[32:33], v[8:9]
	v_pk_fma_f32 v[10:11], v[70:71], v[34:35], v[10:11]
	global_store_dwordx4 v160, v[8:11], s[40:41] offset:1024 nt
	v_lshlrev_b32_e32 v32, 16, v50
	v_and_b32_e32 v33, 0xffff0000, v50
	v_lshlrev_b32_e32 v34, 16, v51
	v_and_b32_e32 v35, 0xffff0000, v51
	v_pk_mul_f32 v[32:33], v[32:33], v[164:165] op_sel_hi:[1,0]
	v_pk_mul_f32 v[34:35], v[34:35], v[164:165] op_sel_hi:[1,0]
	v_pk_mul_f32 v[32:33], v[226:227], v[32:33]
	v_pk_mul_f32 v[34:35], v[228:229], v[34:35]
	s_waitcnt vmcnt(23)
	v_pk_fma_f32 v[4:5], v[72:73], v[32:33], v[4:5]
	v_pk_fma_f32 v[6:7], v[74:75], v[34:35], v[6:7]
	global_store_dwordx4 v160, v[4:7], s[40:41] offset:2048 nt
	v_lshlrev_b32_e32 v32, 16, v48
	v_and_b32_e32 v33, 0xffff0000, v48
	v_lshlrev_b32_e32 v34, 16, v49
	v_and_b32_e32 v35, 0xffff0000, v49
	v_pk_mul_f32 v[32:33], v[32:33], v[164:165] op_sel_hi:[1,0]
	v_pk_mul_f32 v[34:35], v[34:35], v[164:165] op_sel_hi:[1,0]
	v_pk_mul_f32 v[32:33], v[230:231], v[32:33]
	v_pk_mul_f32 v[34:35], v[232:233], v[34:35]
	s_waitcnt vmcnt(23)
	v_pk_fma_f32 v[0:1], v[76:77], v[32:33], v[0:1]
	v_pk_fma_f32 v[2:3], v[78:79], v[34:35], v[2:3]
	global_store_dwordx4 v160, v[0:3], s[40:41] offset:3072 nt
	global_load_dwordx4 v[64:67], v160, s[50:51]
	global_load_dwordx4 v[68:71], v160, s[50:51] offset:1024
	global_load_dwordx4 v[72:75], v160, s[50:51] offset:2048
	global_load_dwordx4 v[76:79], v160, s[50:51] offset:3072
	v_add_co_u32_e32 v250, vcc, 0xfbc00000, v46
	v_addc_co_u32_e32 v251, vcc, -1, v47, vcc
	v_pk_mul_f32 v[166:167], v[12:13], v[12:13]
	v_pk_mul_f32 v[168:169], v[14:15], v[14:15]
	v_pk_fma_f32 v[166:167], v[8:9], v[8:9], v[166:167]
	v_pk_fma_f32 v[168:169], v[10:11], v[10:11], v[168:169]
	v_pk_fma_f32 v[166:167], v[4:5], v[4:5], v[166:167]
	v_pk_fma_f32 v[168:169], v[6:7], v[6:7], v[168:169]
	v_pk_fma_f32 v[166:167], v[0:1], v[0:1], v[166:167]
	v_pk_fma_f32 v[168:169], v[2:3], v[2:3], v[168:169]
	v_pk_add_f32 v[166:167], v[166:167], v[168:169]
	s_nop 0
	v_add_f32_e32 v164, v166, v167
	v_mov_b32_e32 v165, v164
	s_nop 1
	v_permlane32_swap_b32_e32 v165, v164
	v_add_f32_e32 v164, v164, v165
	v_mov_b32_e32 v165, v164
	s_nop 1
	v_permlane16_swap_b32_e32 v165, v164
	v_add_f32_e32 v164, v164, v165
	s_nop 1
	v_add_f32_dpp v164, v164, v164 row_ror:8 row_mask:0xf bank_mask:0xf
	s_nop 1
	v_add_f32_dpp v164, v164, v164 row_ror:4 row_mask:0xf bank_mask:0xf
	s_nop 1
	v_add_f32_dpp v164, v164, v164 row_ror:2 row_mask:0xf bank_mask:0xf
	s_nop 1
	v_add_f32_dpp v164, v164, v164 row_ror:1 row_mask:0xf bank_mask:0xf
	s_nop 0
	v_fmamk_f32 v164, v164, 0x3a800000, v200
	v_rsq_f32_e32 v164, v164
	s_nop 0
	v_pk_mul_f32 v[12:13], v[12:13], v[164:165] op_sel_hi:[1,0]
	v_pk_mul_f32 v[14:15], v[14:15], v[164:165] op_sel_hi:[1,0]
	v_pk_mul_f32 v[12:13], v[234:235], v[12:13]
	v_pk_mul_f32 v[14:15], v[236:237], v[14:15]
	s_waitcnt vmcnt(15)
	v_pk_add_f32 v[172:173], v[172:173], 1.0 op_sel_hi:[1,0]
	v_pk_add_f32 v[174:175], v[174:175], 1.0 op_sel_hi:[1,0]
	v_pk_fma_f32 v[12:13], v[172:173], v[12:13], v[80:81]
	v_pk_fma_f32 v[14:15], v[174:175], v[14:15], v[82:83]
	v_cvt_pk_bf16_f32 v12, v12, v13
	v_cvt_pk_bf16_f32 v13, v14, v15
	global_store_dwordx2 v[250:251], v[12:13], off offset:-1536
	global_load_dwordx4 v[80:83], v160, s[52:53]
	v_pk_mul_f32 v[8:9], v[8:9], v[164:165] op_sel_hi:[1,0]
	v_pk_mul_f32 v[10:11], v[10:11], v[164:165] op_sel_hi:[1,0]
	v_pk_mul_f32 v[8:9], v[238:239], v[8:9]
	v_pk_mul_f32 v[10:11], v[240:241], v[10:11]
	s_waitcnt vmcnt(16)
	v_pk_add_f32 v[176:177], v[176:177], 1.0 op_sel_hi:[1,0]
	v_pk_add_f32 v[178:179], v[178:179], 1.0 op_sel_hi:[1,0]
	v_pk_fma_f32 v[8:9], v[176:177], v[8:9], v[84:85]
	v_pk_fma_f32 v[10:11], v[178:179], v[10:11], v[86:87]
	v_cvt_pk_bf16_f32 v8, v8, v9
	v_cvt_pk_bf16_f32 v9, v10, v11
	global_store_dwordx2 v[250:251], v[8:9], off offset:-1024
	global_load_dwordx4 v[84:87], v160, s[52:53] offset:1024
	v_pk_mul_f32 v[4:5], v[4:5], v[164:165] op_sel_hi:[1,0]
	v_pk_mul_f32 v[6:7], v[6:7], v[164:165] op_sel_hi:[1,0]
	v_pk_mul_f32 v[4:5], v[242:243], v[4:5]
	v_pk_mul_f32 v[6:7], v[244:245], v[6:7]
	s_waitcnt vmcnt(17)
	v_pk_add_f32 v[180:181], v[180:181], 1.0 op_sel_hi:[1,0]
	v_pk_add_f32 v[182:183], v[182:183], 1.0 op_sel_hi:[1,0]
	v_pk_fma_f32 v[4:5], v[180:181], v[4:5], v[88:89]
	v_pk_fma_f32 v[6:7], v[182:183], v[6:7], v[90:91]
	v_cvt_pk_bf16_f32 v4, v4, v5
	v_cvt_pk_bf16_f32 v5, v6, v7
	global_store_dwordx2 v[250:251], v[4:5], off offset:-512
	global_load_dwordx4 v[88:91], v160, s[52:53] offset:2048
	v_pk_mul_f32 v[0:1], v[0:1], v[164:165] op_sel_hi:[1,0]
	v_pk_mul_f32 v[2:3], v[2:3], v[164:165] op_sel_hi:[1,0]
	v_pk_mul_f32 v[0:1], v[246:247], v[0:1]
	v_pk_mul_f32 v[2:3], v[248:249], v[2:3]
	s_waitcnt vmcnt(18)
	v_pk_add_f32 v[184:185], v[184:185], 1.0 op_sel_hi:[1,0]
	v_pk_add_f32 v[186:187], v[186:187], 1.0 op_sel_hi:[1,0]
	v_pk_fma_f32 v[0:1], v[184:185], v[0:1], v[92:93]
	v_pk_fma_f32 v[2:3], v[186:187], v[2:3], v[94:95]
	v_cvt_pk_bf16_f32 v0, v0, v1
	v_cvt_pk_bf16_f32 v1, v2, v3
	global_store_dwordx2 v[250:251], v[0:1], off
	global_load_dwordx4 v[92:95], v160, s[52:53] offset:3072
	s_waitcnt vmcnt(28)
; __device__ __forceinline__ float bflo(unsigned w) { return __uint_as_float(w << 16); }
; __device__ __forceinline__ float bfhi(unsigned w) { return __uint_as_float(w & 0xffff0000u); }
;     __device__ __forceinline__ void init(int N, int G, int c, int latent_only) { lat = latent_only; b.init(latent_only ? NB * SEQ : M, N, G, c); }
;     __device__ __forceinline__ void init(int c_, unsigned* cnt_) { lat.init(NB * SEQ, FF2, 1, 0); c = c_; cnt = cnt_; }
; __device__ __forceinline__ void row_pass(const RowPass& R, int gw, int ngw, int lane) {
;     ...
;             const int row = row0 + k * ngw, bb = bbs[k];
;             if (R.update) {
;                 f32x4 y[4]; float ss = 0.f;
; #pragma unroll
;                 for (int j = 0; j < 4; ++j) { const u32x2 w = yw[k][j]; y[j] = (f32x4){bflo(w.x), bfhi(w.x), bflo(w.y), bfhi(w.y)};
;                     ss += (y[j][0] * y[j][0] + y[j][1] * y[j][1]) + (y[j][2] * y[j][2] + y[j][3] * y[j][3]); }
;                 const float rstd = __builtin_amdgcn_rsqf(wave_sum(ss) * (1.0f / DM) + EPS);
;                 const float* gate = R.mod + ((size_t)(R.lg * 9 + bb) * NMOD + R.gi) * DM;
; #pragma unroll
;                 for (int j = 0; j < 4; ++j) { const f32x4 g = *(const f32x4*)(gate + lane * 4 + 256 * j), gp = *(const f32x4*)(R.gpost + lane * 4 + 256 * j);
;                     v[k][j] = v[k][j] + g * (y[j] * rstd * gp); }
;             }
;             if (R.init || R.update) {
; #pragma unroll
;                 for (int j = 0; j < 4; ++j) __builtin_nontemporal_store(v[k][j], (f32x4*)(xrow[k] + lane * 4 + 256 * j));
	v_lshlrev_b32_e32 v32, 16, v62
	v_and_b32_e32 v33, 0xffff0000, v62
	v_lshlrev_b32_e32 v34, 16, v63
	v_and_b32_e32 v35, 0xffff0000, v63
	v_pk_mul_f32 v[166:167], v[32:33], v[32:33]
	v_pk_mul_f32 v[168:169], v[34:35], v[34:35]
	v_lshlrev_b32_e32 v32, 16, v60
	v_and_b32_e32 v33, 0xffff0000, v60
	v_lshlrev_b32_e32 v34, 16, v61
	v_and_b32_e32 v35, 0xffff0000, v61
	v_pk_fma_f32 v[166:167], v[32:33], v[32:33], v[166:167]
	v_pk_fma_f32 v[168:169], v[34:35], v[34:35], v[168:169]
	v_lshlrev_b32_e32 v32, 16, v58
	v_and_b32_e32 v33, 0xffff0000, v58
	v_lshlrev_b32_e32 v34, 16, v59
	v_and_b32_e32 v35, 0xffff0000, v59
	v_pk_fma_f32 v[166:167], v[32:33], v[32:33], v[166:167]
	v_pk_fma_f32 v[168:169], v[34:35], v[34:35], v[168:169]
	v_lshlrev_b32_e32 v32, 16, v56
	v_and_b32_e32 v33, 0xffff0000, v56
	v_lshlrev_b32_e32 v34, 16, v57
	v_and_b32_e32 v35, 0xffff0000, v57
	v_pk_fma_f32 v[166:167], v[32:33], v[32:33], v[166:167]
	v_pk_fma_f32 v[168:169], v[34:35], v[34:35], v[168:169]
	v_pk_add_f32 v[166:167], v[166:167], v[168:169]
	s_nop 0
	v_add_f32_e32 v164, v166, v167
	v_mov_b32_e32 v165, v164
	s_nop 1
	v_permlane32_swap_b32_e32 v165, v164
	v_add_f32_e32 v164, v164, v165
	v_mov_b32_e32 v165, v164
	s_nop 1
	v_permlane16_swap_b32_e32 v165, v164
	v_add_f32_e32 v164, v164, v165
	s_nop 1
	v_add_f32_dpp v164, v164, v164 row_ror:8 row_mask:0xf bank_mask:0xf
	s_nop 1
	v_add_f32_dpp v164, v164, v164 row_ror:4 row_mask:0xf bank_mask:0xf
	s_nop 1
	v_add_f32_dpp v164, v164, v164 row_ror:2 row_mask:0xf bank_mask:0xf
	s_nop 1
	v_add_f32_dpp v164, v164, v164 row_ror:1 row_mask:0xf bank_mask:0xf
	s_nop 0
	v_fmamk_f32 v164, v164, 0x3a800000, v200
	v_rsq_f32_e32 v164, v164
	v_lshlrev_b32_e32 v32, 16, v62
	v_and_b32_e32 v33, 0xffff0000, v62
	v_lshlrev_b32_e32 v34, 16, v63
	v_and_b32_e32 v35, 0xffff0000, v63
	v_pk_mul_f32 v[32:33], v[32:33], v[164:165] op_sel_hi:[1,0]
	v_pk_mul_f32 v[34:35], v[34:35], v[164:165] op_sel_hi:[1,0]
	v_pk_mul_f32 v[32:33], v[218:219], v[32:33]
	v_pk_mul_f32 v[34:35], v[220:221], v[34:35]
	s_waitcnt vmcnt(19)
	v_pk_fma_f32 v[16:17], v[188:189], v[32:33], v[16:17]
	v_pk_fma_f32 v[18:19], v[190:191], v[34:35], v[18:19]
	global_store_dwordx4 v160, v[16:19], s[64:65] nt
	v_lshlrev_b32_e32 v32, 16, v60
	v_and_b32_e32 v33, 0xffff0000, v60
	v_lshlrev_b32_e32 v34, 16, v61
	v_and_b32_e32 v35, 0xffff0000, v61
	v_pk_mul_f32 v[32:33], v[32:33], v[164:165] op_sel_hi:[1,0]
	v_pk_mul_f32 v[34:35], v[34:35], v[164:165] op_sel_hi:[1,0]
	v_pk_mul_f32 v[32:33], v[222:223], v[32:33]
	v_pk_mul_f32 v[34:35], v[224:225], v[34:35]
	s_waitcnt vmcnt(19)
	v_pk_fma_f32 v[20:21], v[192:193], v[32:33], v[20:21]
	v_pk_fma_f32 v[22:23], v[194:195], v[34:35], v[22:23]
	global_store_dwordx4 v160, v[20:23], s[64:65] offset:1024 nt
	v_lshlrev_b32_e32 v32, 16, v58
	v_and_b32_e32 v33, 0xffff0000, v58
	v_lshlrev_b32_e32 v34, 16, v59
	v_and_b32_e32 v35, 0xffff0000, v59
	v_pk_mul_f32 v[32:33], v[32:33], v[164:165] op_sel_hi:[1,0]
	v_pk_mul_f32 v[34:35], v[34:35], v[164:165] op_sel_hi:[1,0]
	v_pk_mul_f32 v[32:33], v[226:227], v[32:33]
	v_pk_mul_f32 v[34:35], v[228:229], v[34:35]
	s_waitcnt vmcnt(19)
	v_pk_fma_f32 v[24:25], v[196:197], v[32:33], v[24:25]
	v_pk_fma_f32 v[26:27], v[198:199], v[34:35], v[26:27]
	global_store_dwordx4 v160, v[24:27], s[64:65] offset:2048 nt
	v_lshlrev_b32_e32 v32, 16, v56
	v_and_b32_e32 v33, 0xffff0000, v56
	v_lshlrev_b32_e32 v34, 16, v57
	v_and_b32_e32 v35, 0xffff0000, v57
	v_pk_mul_f32 v[32:33], v[32:33], v[164:165] op_sel_hi:[1,0]
	v_pk_mul_f32 v[34:35], v[34:35], v[164:165] op_sel_hi:[1,0]
	v_pk_mul_f32 v[32:33], v[230:231], v[32:33]
	v_pk_mul_f32 v[34:35], v[232:233], v[34:35]
	s_waitcnt vmcnt(19)
	v_pk_fma_f32 v[28:29], v[96:97], v[32:33], v[28:29]
	v_pk_fma_f32 v[30:31], v[98:99], v[34:35], v[30:31]
	global_store_dwordx4 v160, v[28:31], s[64:65] offset:3072 nt
	v_pk_mul_f32 v[166:167], v[16:17], v[16:17]
	v_pk_mul_f32 v[168:169], v[18:19], v[18:19]
	v_pk_fma_f32 v[166:167], v[20:21], v[20:21], v[166:167]
	v_pk_fma_f32 v[168:169], v[22:23], v[22:23], v[168:169]
	v_pk_fma_f32 v[166:167], v[24:25], v[24:25], v[166:167]
	v_pk_fma_f32 v[168:169], v[26:27], v[26:27], v[168:169]
	v_pk_fma_f32 v[166:167], v[28:29], v[28:29], v[166:167]
	v_pk_fma_f32 v[168:169], v[30:31], v[30:31], v[168:169]
	v_pk_add_f32 v[166:167], v[166:167], v[168:169]
	s_nop 0
	v_add_f32_e32 v164, v166, v167
	v_mov_b32_e32 v165, v164
	s_nop 1
	v_permlane32_swap_b32_e32 v165, v164
	v_add_f32_e32 v164, v164, v165
	v_mov_b32_e32 v165, v164
	s_nop 1
	v_permlane16_swap_b32_e32 v165, v164
	v_add_f32_e32 v164, v164, v165
	s_nop 1
	v_add_f32_dpp v164, v164, v164 row_ror:8 row_mask:0xf bank_mask:0xf
	s_nop 1
	v_add_f32_dpp v164, v164, v164 row_ror:4 row_mask:0xf bank_mask:0xf
	s_nop 1
	v_add_f32_dpp v164, v164, v164 row_ror:2 row_mask:0xf bank_mask:0xf
	s_nop 1
	v_add_f32_dpp v164, v164, v164 row_ror:1 row_mask:0xf bank_mask:0xf
	s_nop 0
	v_fmamk_f32 v164, v164, 0x3a800000, v200
	v_rsq_f32_e32 v164, v164
	s_nop 0
	v_pk_mul_f32 v[16:17], v[16:17], v[164:165] op_sel_hi:[1,0]
	v_pk_mul_f32 v[18:19], v[18:19], v[164:165] op_sel_hi:[1,0]
	v_pk_mul_f32 v[16:17], v[234:235], v[16:17]
	v_pk_mul_f32 v[18:19], v[236:237], v[18:19]
	s_waitcnt vmcnt(10)
	v_pk_add_f32 v[80:81], v[80:81], 1.0 op_sel_hi:[1,0]
	v_pk_add_f32 v[82:83], v[82:83], 1.0 op_sel_hi:[1,0]
	v_pk_fma_f32 v[16:17], v[80:81], v[16:17], v[64:65]
	v_pk_fma_f32 v[18:19], v[82:83], v[18:19], v[66:67]
	v_cvt_pk_bf16_f32 v16, v16, v17
	v_cvt_pk_bf16_f32 v17, v18, v19
	global_store_dwordx2 v[252:253], v[16:17], off
	v_pk_mul_f32 v[20:21], v[20:21], v[164:165] op_sel_hi:[1,0]
	v_pk_mul_f32 v[22:23], v[22:23], v[164:165] op_sel_hi:[1,0]
	v_pk_mul_f32 v[20:21], v[238:239], v[20:21]
	v_pk_mul_f32 v[22:23], v[240:241], v[22:23]
	s_waitcnt vmcnt(9)
; __device__ __forceinline__ unsigned pk2(float lo, float hi) { return pg8::cvt_pk_bf16(lo, hi); }
;     __device__ __forceinline__ void init(int N, int G, int c, int latent_only) { lat = latent_only; b.init(latent_only ? NB * SEQ : M, N, G, c); }
;     __device__ __forceinline__ void init(int c_, unsigned* cnt_) { lat.init(NB * SEQ, FF2, 1, 0); c = c_; cnt = cnt_; }
; __device__ __forceinline__ void row_pass(const RowPass& R, int gw, int ngw, int lane) {
;     ...
;     for (int row0 = gw; row0 < M; row0 += NR * ngw) {
;         f32x4 v[NR][4]; u32x2 yw[NR][4]; bool act[NR]; float* xrow[NR]; int bbs[NR];
; #pragma unroll
;         for (int k = 0; k < NR; ++k) {
;             const int row = row0 + k * ngw;
;             const int rowc = row < M ? row : row0;
;             const int b = rowc / RPB, i = rowc - b * RPB; const bool isctx = i < CTXL;
;             act[k] = (row < M) && !(isctx && R.skip_ctx);
;             bbs[k] = isctx ? 8 : b;
;             xrow[k] = isctx ? R.xc + ((size_t)b * CTXL + i) * DM : R.out + ((size_t)b * SEQ + (i - CTXL)) * DM;
;             const float* src = R.init ? (isctx ? R.ctx_in + ((size_t)b * CTXL + i) * DM : R.x_in + ((size_t)b * SEQ + (i - CTXL)) * DM) : xrow[k];
;             if (act[k]) {
; #pragma unroll
;                 for (int j = 0; j < 4; ++j) v[k][j] = __builtin_nontemporal_load((const f32x4*)(src + lane * 4 + 256 * j));
;                 if (R.update) { const bf16* yr = R.Y + (size_t)rowc * DM;
; #pragma unroll
;                     for (int j = 0; j < 4; ++j) yw[k][j] = __builtin_nontemporal_load((const u32x2*)(yr + lane * 4 + 256 * j)); }
;             }
;         }
;     ...
;                 for (int j = 0; j < 4; ++j) { const f32x4 gp = *(const f32x4*)(R.gpre + lane * 4 + 256 * j), sh = *(const f32x4*)(shift + lane * 4 + 256 * j), sc = *(const f32x4*)(scale + lane * 4 + 256 * j);
;                     const f32x4 hv = (v[k][j] * rstd * gp) * (sc + 1.0f) + sh;
;                     u32x2 w; w.x = pk2(hv[0], hv[1]); w.y = pk2(hv[2], hv[3]); *(u32x2*)(hr + lane * 4 + 256 * j) = w; }
;             }
	v_pk_add_f32 v[84:85], v[84:85], 1.0 op_sel_hi:[1,0]
	v_pk_add_f32 v[86:87], v[86:87], 1.0 op_sel_hi:[1,0]
	v_pk_fma_f32 v[20:21], v[84:85], v[20:21], v[68:69]
	v_pk_fma_f32 v[22:23], v[86:87], v[22:23], v[70:71]
	v_cvt_pk_bf16_f32 v20, v20, v21
	v_cvt_pk_bf16_f32 v21, v22, v23
	global_store_dwordx2 v[252:253], v[20:21], off offset:512
	v_pk_mul_f32 v[24:25], v[24:25], v[164:165] op_sel_hi:[1,0]
	v_pk_mul_f32 v[26:27], v[26:27], v[164:165] op_sel_hi:[1,0]
	v_pk_mul_f32 v[24:25], v[242:243], v[24:25]
	v_pk_mul_f32 v[26:27], v[244:245], v[26:27]
	s_waitcnt vmcnt(8)
	v_pk_add_f32 v[88:89], v[88:89], 1.0 op_sel_hi:[1,0]
	v_pk_add_f32 v[90:91], v[90:91], 1.0 op_sel_hi:[1,0]
	v_pk_fma_f32 v[24:25], v[88:89], v[24:25], v[72:73]
	v_pk_fma_f32 v[26:27], v[90:91], v[26:27], v[74:75]
	v_cvt_pk_bf16_f32 v24, v24, v25
	v_cvt_pk_bf16_f32 v25, v26, v27
	global_store_dwordx2 v[252:253], v[24:25], off offset:1024
	v_pk_mul_f32 v[28:29], v[28:29], v[164:165] op_sel_hi:[1,0]
	v_pk_mul_f32 v[30:31], v[30:31], v[164:165] op_sel_hi:[1,0]
	v_pk_mul_f32 v[28:29], v[246:247], v[28:29]
	v_pk_mul_f32 v[30:31], v[248:249], v[30:31]
	s_waitcnt vmcnt(7)
	v_pk_add_f32 v[92:93], v[92:93], 1.0 op_sel_hi:[1,0]
	v_pk_add_f32 v[94:95], v[94:95], 1.0 op_sel_hi:[1,0]
	v_pk_fma_f32 v[28:29], v[92:93], v[28:29], v[76:77]
	v_pk_fma_f32 v[30:31], v[94:95], v[30:31], v[78:79]
	v_cvt_pk_bf16_f32 v28, v28, v29
	v_cvt_pk_bf16_f32 v29, v30, v31
	global_store_dwordx2 v[252:253], v[28:29], off offset:1536
	s_branch .LBB0_131
.Lr2_slow_same:
	s_add_i32 s72, s7, 0xffffff00
	s_cmp_lg_u64 s[50:51], 0
	s_cselect_b32 s27, s4, s49
	s_cselect_b32 s32, s5, s55
	s_cselect_b32 s37, 24, 20
	s_cselect_b32 s72, s72, s7
	s_cselect_b32 s85, s6, 8
	s_mov_b32 s40, s6
	s_mov_b32 s41, 0
	s_lshl_b64 s[40:41], s[40:41], s37
	s_add_u32 s40, s27, s40
	s_addc_u32 s41, s32, s41
	s_lshl_b32 s72, s72, 12
	s_add_u32 s40, s40, s72
	s_addc_u32 s41, s41, 0
	s_add_i32 s27, s85, s3
	s_mul_hi_i32 s32, s27, 0x6000
	s_mulk_i32 s27, 0x6000
	s_add_u32 s66, s34, s27
	s_addc_u32 s67, s35, s32
	s_add_u32 s66, s66, 0x2000
	s_addc_u32 s67, s67, 0
	s_add_i32 s27, s85, s3
	s_mul_hi_i32 s32, s27, 0x6000
	s_mulk_i32 s27, 0x6000
	s_add_u32 s38, s34, s27
	s_addc_u32 s39, s35, s32
	s_add_u32 s38, s38, 0x3000
	s_addc_u32 s39, s39, 0
	s_add_u32 s46, s38, 0x1000
	s_addc_u32 s47, s39, 0
	global_load_dwordx4 v[12:15], v160, s[40:41] nt
	global_load_dwordx4 v[8:11], v160, s[40:41] offset:1024 nt
	global_load_dwordx4 v[4:7], v160, s[40:41] offset:2048 nt
	global_load_dwordx4 v[0:3], v160, s[40:41] offset:3072 nt
	global_load_dwordx2 v[54:55], v[46:47], off offset:-1536 nt
	global_load_dwordx2 v[52:53], v[46:47], off offset:-1024 nt
	global_load_dwordx2 v[50:51], v[46:47], off offset:-512 nt
	global_load_dwordx2 v[48:49], v[46:47], off nt
	global_load_dwordx4 v[64:67], v160, s[66:67]
	global_load_dwordx4 v[68:71], v160, s[66:67] offset:1024
	global_load_dwordx4 v[72:75], v160, s[66:67] offset:2048
	global_load_dwordx4 v[76:79], v160, s[66:67] offset:3072
	s_mov_b32 s6, s8
	s_ashr_i32 s7, s8, 31
	s_lshl_b64 s[6:7], s[6:7], 11
	v_lshl_add_u64 v[250:251], v[38:39], 0, s[6:7]
	v_lshl_add_u64 v[252:253], v[40:41], 0, s[6:7]
	s_mov_b64 s[6:7], s[52:53]
	s_add_i32 s72, s25, 0xffffff00
	s_cmp_lg_u64 s[6:7], 0
	s_cselect_b32 s27, s4, s49
	s_cselect_b32 s32, s5, s55
	s_cselect_b32 s37, 24, 20
	s_cselect_b32 s72, s72, s25
	s_cselect_b32 s85, s9, 8
	s_mov_b32 s64, s9
	s_mov_b32 s65, 0
	s_lshl_b64 s[64:65], s[64:65], s37
	s_add_u32 s64, s27, s64
	s_addc_u32 s65, s32, s65
	s_lshl_b32 s72, s72, 12
	s_add_u32 s64, s64, s72
	s_addc_u32 s65, s65, 0
	s_add_i32 s27, s85, s3
	s_mul_hi_i32 s32, s27, 0x6000
	s_mulk_i32 s27, 0x6000
	s_add_u32 s10, s34, s27
	s_addc_u32 s11, s35, s32
	s_add_u32 s10, s10, 0x2000
	s_addc_u32 s11, s11, 0
	s_add_i32 s27, s85, s3
	s_mul_hi_i32 s32, s27, 0x6000
	s_mulk_i32 s27, 0x6000
	s_add_u32 s50, s34, s27
	s_addc_u32 s51, s35, s32
	s_add_u32 s50, s50, 0x3000
	s_addc_u32 s51, s51, 0
	s_add_u32 s52, s50, 0x1000
	s_addc_u32 s53, s51, 0
	global_load_dwordx4 v[16:19], v160, s[64:65] nt
	global_load_dwordx4 v[20:23], v160, s[64:65] offset:1024 nt
	global_load_dwordx4 v[24:27], v160, s[64:65] offset:2048 nt
	global_load_dwordx4 v[28:31], v160, s[64:65] offset:3072 nt
	global_load_dwordx2 v[62:63], v[250:251], off nt
	global_load_dwordx2 v[60:61], v[250:251], off offset:512 nt
	global_load_dwordx2 v[58:59], v[250:251], off offset:1024 nt
	global_load_dwordx2 v[56:57], v[250:251], off offset:1536 nt
	global_load_dwordx4 v[80:83], v160, s[38:39]
	global_load_dwordx4 v[84:87], v160, s[38:39] offset:1024
	global_load_dwordx4 v[88:91], v160, s[38:39] offset:2048
	global_load_dwordx4 v[92:95], v160, s[38:39] offset:3072
	global_load_dwordx4 v[172:175], v160, s[46:47]
	global_load_dwordx4 v[176:179], v160, s[46:47] offset:1024
	global_load_dwordx4 v[180:183], v160, s[46:47] offset:2048
	global_load_dwordx4 v[184:187], v160, s[46:47] offset:3072
	s_waitcnt vmcnt(20)
; __device__ __forceinline__ unsigned pk2(float lo, float hi) { return pg8::cvt_pk_bf16(lo, hi); }
; __device__ __forceinline__ float bflo(unsigned w) { return __uint_as_float(w << 16); }
; __device__ __forceinline__ float bfhi(unsigned w) { return __uint_as_float(w & 0xffff0000u); }
; __device__ __forceinline__ void row_pass(const RowPass& R, int gw, int ngw, int lane) {
;     ...
;             const int row = row0 + k * ngw, bb = bbs[k];
;             if (R.update) {
;                 f32x4 y[4]; float ss = 0.f;
; #pragma unroll
;                 for (int j = 0; j < 4; ++j) { const u32x2 w = yw[k][j]; y[j] = (f32x4){bflo(w.x), bfhi(w.x), bflo(w.y), bfhi(w.y)};
;                     ss += (y[j][0] * y[j][0] + y[j][1] * y[j][1]) + (y[j][2] * y[j][2] + y[j][3] * y[j][3]); }
;                 const float rstd = __builtin_amdgcn_rsqf(wave_sum(ss) * (1.0f / DM) + EPS);
;                 const float* gate = R.mod + ((size_t)(R.lg * 9 + bb) * NMOD + R.gi) * DM;
; #pragma unroll
;                 for (int j = 0; j < 4; ++j) { const f32x4 g = *(const f32x4*)(gate + lane * 4 + 256 * j), gp = *(const f32x4*)(R.gpost + lane * 4 + 256 * j);
;                     v[k][j] = v[k][j] + g * (y[j] * rstd * gp); }
;             }
;             if (R.init || R.update) {
; #pragma unroll
;                 for (int j = 0; j < 4; ++j) __builtin_nontemporal_store(v[k][j], (f32x4*)(xrow[k] + lane * 4 + 256 * j));
;             }
;             if (R.norm_out) {
;                 float ss = 0.f;
; #pragma unroll
;                 for (int j = 0; j < 4; ++j) ss += (v[k][j][0] * v[k][j][0] + v[k][j][1] * v[k][j][1]) + (v[k][j][2] * v[k][j][2] + v[k][j][3] * v[k][j][3]);
;                 const float rstd = __builtin_amdgcn_rsqf(wave_sum(ss) * (1.0f / DM) + EPS);
;                 const float* shift = R.mod + ((size_t)(R.ln * 9 + bb) * NMOD + R.si) * DM; const float* scale = shift + DM;
;                 bf16* hr = R.H + (size_t)row * DM;
; #pragma unroll
;                 for (int j = 0; j < 4; ++j) { const f32x4 gp = *(const f32x4*)(R.gpre + lane * 4 + 256 * j), sh = *(const f32x4*)(shift + lane * 4 + 256 * j), sc = *(const f32x4*)(scale + lane * 4 + 256 * j);
;                     const f32x4 hv = (v[k][j] * rstd * gp) * (sc + 1.0f) + sh;
;                     u32x2 w; w.x = pk2(hv[0], hv[1]); w.y = pk2(hv[2], hv[3]); *(u32x2*)(hr + lane * 4 + 256 * j) = w; }
;             }
	v_lshlrev_b32_e32 v32, 16, v54
	v_and_b32_e32 v33, 0xffff0000, v54
	v_lshlrev_b32_e32 v34, 16, v55
	v_and_b32_e32 v35, 0xffff0000, v55
	v_pk_mul_f32 v[166:167], v[32:33], v[32:33]
	v_pk_mul_f32 v[168:169], v[34:35], v[34:35]
	v_lshlrev_b32_e32 v32, 16, v52
	v_and_b32_e32 v33, 0xffff0000, v52
	v_lshlrev_b32_e32 v34, 16, v53
	v_and_b32_e32 v35, 0xffff0000, v53
	v_pk_fma_f32 v[166:167], v[32:33], v[32:33], v[166:167]
	v_pk_fma_f32 v[168:169], v[34:35], v[34:35], v[168:169]
	v_lshlrev_b32_e32 v32, 16, v50
	v_and_b32_e32 v33, 0xffff0000, v50
	v_lshlrev_b32_e32 v34, 16, v51
	v_and_b32_e32 v35, 0xffff0000, v51
	v_pk_fma_f32 v[166:167], v[32:33], v[32:33], v[166:167]
	v_pk_fma_f32 v[168:169], v[34:35], v[34:35], v[168:169]
	v_lshlrev_b32_e32 v32, 16, v48
	v_and_b32_e32 v33, 0xffff0000, v48
	v_lshlrev_b32_e32 v34, 16, v49
	v_and_b32_e32 v35, 0xffff0000, v49
	v_pk_fma_f32 v[166:167], v[32:33], v[32:33], v[166:167]
	v_pk_fma_f32 v[168:169], v[34:35], v[34:35], v[168:169]
	v_pk_add_f32 v[166:167], v[166:167], v[168:169]
	s_nop 0
	v_add_f32_e32 v164, v166, v167
	v_mov_b32_e32 v165, v164
	s_nop 1
	v_permlane32_swap_b32_e32 v165, v164
	v_add_f32_e32 v164, v164, v165
	v_mov_b32_e32 v165, v164
	s_nop 1
	v_permlane16_swap_b32_e32 v165, v164
	v_add_f32_e32 v164, v164, v165
	s_nop 1
	v_add_f32_dpp v164, v164, v164 row_ror:8 row_mask:0xf bank_mask:0xf
	s_nop 1
	v_add_f32_dpp v164, v164, v164 row_ror:4 row_mask:0xf bank_mask:0xf
	s_nop 1
	v_add_f32_dpp v164, v164, v164 row_ror:2 row_mask:0xf bank_mask:0xf
	s_nop 1
	v_add_f32_dpp v164, v164, v164 row_ror:1 row_mask:0xf bank_mask:0xf
	s_nop 0
	v_fmamk_f32 v164, v164, 0x3a800000, v200
	v_rsq_f32_e32 v164, v164
	v_lshlrev_b32_e32 v32, 16, v54
	v_and_b32_e32 v33, 0xffff0000, v54
	v_lshlrev_b32_e32 v34, 16, v55
	v_and_b32_e32 v35, 0xffff0000, v55
	v_pk_mul_f32 v[32:33], v[32:33], v[164:165] op_sel_hi:[1,0]
	v_pk_mul_f32 v[34:35], v[34:35], v[164:165] op_sel_hi:[1,0]
	v_pk_mul_f32 v[32:33], v[218:219], v[32:33]
	v_pk_mul_f32 v[34:35], v[220:221], v[34:35]
	s_waitcnt vmcnt(19)
	v_pk_fma_f32 v[12:13], v[64:65], v[32:33], v[12:13]
	v_pk_fma_f32 v[14:15], v[66:67], v[34:35], v[14:15]
	global_store_dwordx4 v160, v[12:15], s[40:41] nt
	v_lshlrev_b32_e32 v32, 16, v52
	v_and_b32_e32 v33, 0xffff0000, v52
	v_lshlrev_b32_e32 v34, 16, v53
	v_and_b32_e32 v35, 0xffff0000, v53
	v_pk_mul_f32 v[32:33], v[32:33], v[164:165] op_sel_hi:[1,0]
	v_pk_mul_f32 v[34:35], v[34:35], v[164:165] op_sel_hi:[1,0]
	v_pk_mul_f32 v[32:33], v[222:223], v[32:33]
	v_pk_mul_f32 v[34:35], v[224:225], v[34:35]
	s_waitcnt vmcnt(19)
	v_pk_fma_f32 v[8:9], v[68:69], v[32:33], v[8:9]
	v_pk_fma_f32 v[10:11], v[70:71], v[34:35], v[10:11]
	global_store_dwordx4 v160, v[8:11], s[40:41] offset:1024 nt
	v_lshlrev_b32_e32 v32, 16, v50
	v_and_b32_e32 v33, 0xffff0000, v50
	v_lshlrev_b32_e32 v34, 16, v51
	v_and_b32_e32 v35, 0xffff0000, v51
	v_pk_mul_f32 v[32:33], v[32:33], v[164:165] op_sel_hi:[1,0]
	v_pk_mul_f32 v[34:35], v[34:35], v[164:165] op_sel_hi:[1,0]
	v_pk_mul_f32 v[32:33], v[226:227], v[32:33]
	v_pk_mul_f32 v[34:35], v[228:229], v[34:35]
	s_waitcnt vmcnt(19)
	v_pk_fma_f32 v[4:5], v[72:73], v[32:33], v[4:5]
	v_pk_fma_f32 v[6:7], v[74:75], v[34:35], v[6:7]
	global_store_dwordx4 v160, v[4:7], s[40:41] offset:2048 nt
	v_lshlrev_b32_e32 v32, 16, v48
	v_and_b32_e32 v33, 0xffff0000, v48
	v_lshlrev_b32_e32 v34, 16, v49
	v_and_b32_e32 v35, 0xffff0000, v49
	v_pk_mul_f32 v[32:33], v[32:33], v[164:165] op_sel_hi:[1,0]
	v_pk_mul_f32 v[34:35], v[34:35], v[164:165] op_sel_hi:[1,0]
	v_pk_mul_f32 v[32:33], v[230:231], v[32:33]
	v_pk_mul_f32 v[34:35], v[232:233], v[34:35]
	s_waitcnt vmcnt(19)
	v_pk_fma_f32 v[0:1], v[76:77], v[32:33], v[0:1]
	v_pk_fma_f32 v[2:3], v[78:79], v[34:35], v[2:3]
	global_store_dwordx4 v160, v[0:3], s[40:41] offset:3072 nt
	v_add_co_u32_e32 v250, vcc, 0xfbc00000, v46
	v_addc_co_u32_e32 v251, vcc, -1, v47, vcc
	v_pk_mul_f32 v[166:167], v[12:13], v[12:13]
	v_pk_mul_f32 v[168:169], v[14:15], v[14:15]
	v_pk_fma_f32 v[166:167], v[8:9], v[8:9], v[166:167]
	v_pk_fma_f32 v[168:169], v[10:11], v[10:11], v[168:169]
	v_pk_fma_f32 v[166:167], v[4:5], v[4:5], v[166:167]
	v_pk_fma_f32 v[168:169], v[6:7], v[6:7], v[168:169]
	v_pk_fma_f32 v[166:167], v[0:1], v[0:1], v[166:167]
	v_pk_fma_f32 v[168:169], v[2:3], v[2:3], v[168:169]
	v_pk_add_f32 v[166:167], v[166:167], v[168:169]
	s_nop 0
	v_add_f32_e32 v164, v166, v167
	v_mov_b32_e32 v165, v164
	s_nop 1
	v_permlane32_swap_b32_e32 v165, v164
	v_add_f32_e32 v164, v164, v165
	v_mov_b32_e32 v165, v164
	s_nop 1
	v_permlane16_swap_b32_e32 v165, v164
	v_add_f32_e32 v164, v164, v165
	s_nop 1
	v_add_f32_dpp v164, v164, v164 row_ror:8 row_mask:0xf bank_mask:0xf
	s_nop 1
	v_add_f32_dpp v164, v164, v164 row_ror:4 row_mask:0xf bank_mask:0xf
	s_nop 1
	v_add_f32_dpp v164, v164, v164 row_ror:2 row_mask:0xf bank_mask:0xf
	s_nop 1
	v_add_f32_dpp v164, v164, v164 row_ror:1 row_mask:0xf bank_mask:0xf
	s_nop 0
	v_fmamk_f32 v164, v164, 0x3a800000, v200
	v_rsq_f32_e32 v164, v164
	s_nop 0
	v_pk_mul_f32 v[12:13], v[12:13], v[164:165] op_sel_hi:[1,0]
	v_pk_mul_f32 v[14:15], v[14:15], v[164:165] op_sel_hi:[1,0]
	v_pk_mul_f32 v[12:13], v[234:235], v[12:13]
	v_pk_mul_f32 v[14:15], v[236:237], v[14:15]
	s_waitcnt vmcnt(7)
	v_pk_add_f32 v[172:173], v[172:173], 1.0 op_sel_hi:[1,0]
	v_pk_add_f32 v[174:175], v[174:175], 1.0 op_sel_hi:[1,0]
	v_pk_fma_f32 v[12:13], v[172:173], v[12:13], v[80:81]
	v_pk_fma_f32 v[14:15], v[174:175], v[14:15], v[82:83]
	v_cvt_pk_bf16_f32 v12, v12, v13
	v_cvt_pk_bf16_f32 v13, v14, v15
	global_store_dwordx2 v[250:251], v[12:13], off offset:-1536
	v_pk_mul_f32 v[8:9], v[8:9], v[164:165] op_sel_hi:[1,0]
	v_pk_mul_f32 v[10:11], v[10:11], v[164:165] op_sel_hi:[1,0]
	v_pk_mul_f32 v[8:9], v[238:239], v[8:9]
	v_pk_mul_f32 v[10:11], v[240:241], v[10:11]
	s_waitcnt vmcnt(7)
; __device__ __forceinline__ unsigned pk2(float lo, float hi) { return pg8::cvt_pk_bf16(lo, hi); }
; __device__ __forceinline__ float bflo(unsigned w) { return __uint_as_float(w << 16); }
; __device__ __forceinline__ float bfhi(unsigned w) { return __uint_as_float(w & 0xffff0000u); }
;     __device__ __forceinline__ void init(int N, int G, int c, int latent_only) { lat = latent_only; b.init(latent_only ? NB * SEQ : M, N, G, c); }
; __device__ __forceinline__ void row_pass(const RowPass& R, int gw, int ngw, int lane) {
;     ...
;                 for (int j = 0; j < 4; ++j) { const u32x2 w = yw[k][j]; y[j] = (f32x4){bflo(w.x), bfhi(w.x), bflo(w.y), bfhi(w.y)};
;                     ss += (y[j][0] * y[j][0] + y[j][1] * y[j][1]) + (y[j][2] * y[j][2] + y[j][3] * y[j][3]); }
;                 const float rstd = __builtin_amdgcn_rsqf(wave_sum(ss) * (1.0f / DM) + EPS);
;                 const float* gate = R.mod + ((size_t)(R.lg * 9 + bb) * NMOD + R.gi) * DM;
; #pragma unroll
;                 for (int j = 0; j < 4; ++j) { const f32x4 g = *(const f32x4*)(gate + lane * 4 + 256 * j), gp = *(const f32x4*)(R.gpost + lane * 4 + 256 * j);
;                     v[k][j] = v[k][j] + g * (y[j] * rstd * gp); }
;             }
;             if (R.init || R.update) {
; #pragma unroll
;                 for (int j = 0; j < 4; ++j) __builtin_nontemporal_store(v[k][j], (f32x4*)(xrow[k] + lane * 4 + 256 * j));
;             }
;             if (R.norm_out) {
;                 float ss = 0.f;
; #pragma unroll
;                 for (int j = 0; j < 4; ++j) ss += (v[k][j][0] * v[k][j][0] + v[k][j][1] * v[k][j][1]) + (v[k][j][2] * v[k][j][2] + v[k][j][3] * v[k][j][3]);
;                 const float rstd = __builtin_amdgcn_rsqf(wave_sum(ss) * (1.0f / DM) + EPS);
;                 const float* shift = R.mod + ((size_t)(R.ln * 9 + bb) * NMOD + R.si) * DM; const float* scale = shift + DM;
;                 bf16* hr = R.H + (size_t)row * DM;
; #pragma unroll
;                 for (int j = 0; j < 4; ++j) { const f32x4 gp = *(const f32x4*)(R.gpre + lane * 4 + 256 * j), sh = *(const f32x4*)(shift + lane * 4 + 256 * j), sc = *(const f32x4*)(scale + lane * 4 + 256 * j);
;                     const f32x4 hv = (v[k][j] * rstd * gp) * (sc + 1.0f) + sh;
;                     u32x2 w; w.x = pk2(hv[0], hv[1]); w.y = pk2(hv[2], hv[3]); *(u32x2*)(hr + lane * 4 + 256 * j) = w; }
	v_pk_add_f32 v[176:177], v[176:177], 1.0 op_sel_hi:[1,0]
	v_pk_add_f32 v[178:179], v[178:179], 1.0 op_sel_hi:[1,0]
	v_pk_fma_f32 v[8:9], v[176:177], v[8:9], v[84:85]
	v_pk_fma_f32 v[10:11], v[178:179], v[10:11], v[86:87]
	v_cvt_pk_bf16_f32 v8, v8, v9
	v_cvt_pk_bf16_f32 v9, v10, v11
	global_store_dwordx2 v[250:251], v[8:9], off offset:-1024
	v_pk_mul_f32 v[4:5], v[4:5], v[164:165] op_sel_hi:[1,0]
	v_pk_mul_f32 v[6:7], v[6:7], v[164:165] op_sel_hi:[1,0]
	v_pk_mul_f32 v[4:5], v[242:243], v[4:5]
	v_pk_mul_f32 v[6:7], v[244:245], v[6:7]
	s_waitcnt vmcnt(7)
	v_pk_add_f32 v[180:181], v[180:181], 1.0 op_sel_hi:[1,0]
	v_pk_add_f32 v[182:183], v[182:183], 1.0 op_sel_hi:[1,0]
	v_pk_fma_f32 v[4:5], v[180:181], v[4:5], v[88:89]
	v_pk_fma_f32 v[6:7], v[182:183], v[6:7], v[90:91]
	v_cvt_pk_bf16_f32 v4, v4, v5
	v_cvt_pk_bf16_f32 v5, v6, v7
	global_store_dwordx2 v[250:251], v[4:5], off offset:-512
	v_pk_mul_f32 v[0:1], v[0:1], v[164:165] op_sel_hi:[1,0]
	v_pk_mul_f32 v[2:3], v[2:3], v[164:165] op_sel_hi:[1,0]
	v_pk_mul_f32 v[0:1], v[246:247], v[0:1]
	v_pk_mul_f32 v[2:3], v[248:249], v[2:3]
	s_waitcnt vmcnt(7)
	v_pk_add_f32 v[184:185], v[184:185], 1.0 op_sel_hi:[1,0]
	v_pk_add_f32 v[186:187], v[186:187], 1.0 op_sel_hi:[1,0]
	v_pk_fma_f32 v[0:1], v[184:185], v[0:1], v[92:93]
	v_pk_fma_f32 v[2:3], v[186:187], v[2:3], v[94:95]
	v_cvt_pk_bf16_f32 v0, v0, v1
	v_cvt_pk_bf16_f32 v1, v2, v3
	global_store_dwordx2 v[250:251], v[0:1], off
	s_waitcnt vmcnt(16)
	v_lshlrev_b32_e32 v32, 16, v62
	v_and_b32_e32 v33, 0xffff0000, v62
	v_lshlrev_b32_e32 v34, 16, v63
	v_and_b32_e32 v35, 0xffff0000, v63
	v_pk_mul_f32 v[166:167], v[32:33], v[32:33]
	v_pk_mul_f32 v[168:169], v[34:35], v[34:35]
	v_lshlrev_b32_e32 v32, 16, v60
	v_and_b32_e32 v33, 0xffff0000, v60
	v_lshlrev_b32_e32 v34, 16, v61
	v_and_b32_e32 v35, 0xffff0000, v61
	v_pk_fma_f32 v[166:167], v[32:33], v[32:33], v[166:167]
	v_pk_fma_f32 v[168:169], v[34:35], v[34:35], v[168:169]
	v_lshlrev_b32_e32 v32, 16, v58
	v_and_b32_e32 v33, 0xffff0000, v58
	v_lshlrev_b32_e32 v34, 16, v59
	v_and_b32_e32 v35, 0xffff0000, v59
	v_pk_fma_f32 v[166:167], v[32:33], v[32:33], v[166:167]
	v_pk_fma_f32 v[168:169], v[34:35], v[34:35], v[168:169]
	v_lshlrev_b32_e32 v32, 16, v56
	v_and_b32_e32 v33, 0xffff0000, v56
	v_lshlrev_b32_e32 v34, 16, v57
	v_and_b32_e32 v35, 0xffff0000, v57
	v_pk_fma_f32 v[166:167], v[32:33], v[32:33], v[166:167]
	v_pk_fma_f32 v[168:169], v[34:35], v[34:35], v[168:169]
	v_pk_add_f32 v[166:167], v[166:167], v[168:169]
	s_nop 0
	v_add_f32_e32 v164, v166, v167
	v_mov_b32_e32 v165, v164
	s_nop 1
	v_permlane32_swap_b32_e32 v165, v164
	v_add_f32_e32 v164, v164, v165
	v_mov_b32_e32 v165, v164
	s_nop 1
	v_permlane16_swap_b32_e32 v165, v164
	v_add_f32_e32 v164, v164, v165
	s_nop 1
	v_add_f32_dpp v164, v164, v164 row_ror:8 row_mask:0xf bank_mask:0xf
	s_nop 1
	v_add_f32_dpp v164, v164, v164 row_ror:4 row_mask:0xf bank_mask:0xf
	s_nop 1
	v_add_f32_dpp v164, v164, v164 row_ror:2 row_mask:0xf bank_mask:0xf
	s_nop 1
	v_add_f32_dpp v164, v164, v164 row_ror:1 row_mask:0xf bank_mask:0xf
	s_nop 0
	v_fmamk_f32 v164, v164, 0x3a800000, v200
	v_rsq_f32_e32 v164, v164
	v_lshlrev_b32_e32 v32, 16, v62
	v_and_b32_e32 v33, 0xffff0000, v62
	v_lshlrev_b32_e32 v34, 16, v63
	v_and_b32_e32 v35, 0xffff0000, v63
	v_pk_mul_f32 v[32:33], v[32:33], v[164:165] op_sel_hi:[1,0]
	v_pk_mul_f32 v[34:35], v[34:35], v[164:165] op_sel_hi:[1,0]
	v_pk_mul_f32 v[32:33], v[218:219], v[32:33]
	v_pk_mul_f32 v[34:35], v[220:221], v[34:35]
	s_waitcnt vmcnt(27)
	v_pk_fma_f32 v[16:17], v[64:65], v[32:33], v[16:17]
	v_pk_fma_f32 v[18:19], v[66:67], v[34:35], v[18:19]
	global_store_dwordx4 v160, v[16:19], s[64:65] nt
	v_lshlrev_b32_e32 v32, 16, v60
	v_and_b32_e32 v33, 0xffff0000, v60
	v_lshlrev_b32_e32 v34, 16, v61
	v_and_b32_e32 v35, 0xffff0000, v61
	v_pk_mul_f32 v[32:33], v[32:33], v[164:165] op_sel_hi:[1,0]
	v_pk_mul_f32 v[34:35], v[34:35], v[164:165] op_sel_hi:[1,0]
	v_pk_mul_f32 v[32:33], v[222:223], v[32:33]
	v_pk_mul_f32 v[34:35], v[224:225], v[34:35]
	s_waitcnt vmcnt(27)
; __device__ __forceinline__ unsigned pk2(float lo, float hi) { return pg8::cvt_pk_bf16(lo, hi); }
;     __device__ __forceinline__ void init(int N, int G, int c, int latent_only) { lat = latent_only; b.init(latent_only ? NB * SEQ : M, N, G, c); }
;     __device__ __forceinline__ void init(int c_, unsigned* cnt_) { lat.init(NB * SEQ, FF2, 1, 0); c = c_; cnt = cnt_; }
; __device__ __forceinline__ void row_pass(const RowPass& R, int gw, int ngw, int lane) {
;     ...
;                 for (int j = 0; j < 4; ++j) { const f32x4 g = *(const f32x4*)(gate + lane * 4 + 256 * j), gp = *(const f32x4*)(R.gpost + lane * 4 + 256 * j);
;                     v[k][j] = v[k][j] + g * (y[j] * rstd * gp); }
;             }
;             if (R.init || R.update) {
; #pragma unroll
;                 for (int j = 0; j < 4; ++j) __builtin_nontemporal_store(v[k][j], (f32x4*)(xrow[k] + lane * 4 + 256 * j));
;             }
;             if (R.norm_out) {
;                 float ss = 0.f;
; #pragma unroll
;                 for (int j = 0; j < 4; ++j) ss += (v[k][j][0] * v[k][j][0] + v[k][j][1] * v[k][j][1]) + (v[k][j][2] * v[k][j][2] + v[k][j][3] * v[k][j][3]);
;                 const float rstd = __builtin_amdgcn_rsqf(wave_sum(ss) * (1.0f / DM) + EPS);
;                 const float* shift = R.mod + ((size_t)(R.ln * 9 + bb) * NMOD + R.si) * DM; const float* scale = shift + DM;
;                 bf16* hr = R.H + (size_t)row * DM;
; #pragma unroll
;                 for (int j = 0; j < 4; ++j) { const f32x4 gp = *(const f32x4*)(R.gpre + lane * 4 + 256 * j), sh = *(const f32x4*)(shift + lane * 4 + 256 * j), sc = *(const f32x4*)(scale + lane * 4 + 256 * j);
;                     const f32x4 hv = (v[k][j] * rstd * gp) * (sc + 1.0f) + sh;
;                     u32x2 w; w.x = pk2(hv[0], hv[1]); w.y = pk2(hv[2], hv[3]); *(u32x2*)(hr + lane * 4 + 256 * j) = w; }
	v_pk_fma_f32 v[20:21], v[68:69], v[32:33], v[20:21]
	v_pk_fma_f32 v[22:23], v[70:71], v[34:35], v[22:23]
	global_store_dwordx4 v160, v[20:23], s[64:65] offset:1024 nt
	v_lshlrev_b32_e32 v32, 16, v58
	v_and_b32_e32 v33, 0xffff0000, v58
	v_lshlrev_b32_e32 v34, 16, v59
	v_and_b32_e32 v35, 0xffff0000, v59
	v_pk_mul_f32 v[32:33], v[32:33], v[164:165] op_sel_hi:[1,0]
	v_pk_mul_f32 v[34:35], v[34:35], v[164:165] op_sel_hi:[1,0]
	v_pk_mul_f32 v[32:33], v[226:227], v[32:33]
	v_pk_mul_f32 v[34:35], v[228:229], v[34:35]
	s_waitcnt vmcnt(27)
	v_pk_fma_f32 v[24:25], v[72:73], v[32:33], v[24:25]
	v_pk_fma_f32 v[26:27], v[74:75], v[34:35], v[26:27]
	global_store_dwordx4 v160, v[24:27], s[64:65] offset:2048 nt
	v_lshlrev_b32_e32 v32, 16, v56
	v_and_b32_e32 v33, 0xffff0000, v56
	v_lshlrev_b32_e32 v34, 16, v57
	v_and_b32_e32 v35, 0xffff0000, v57
	v_pk_mul_f32 v[32:33], v[32:33], v[164:165] op_sel_hi:[1,0]
	v_pk_mul_f32 v[34:35], v[34:35], v[164:165] op_sel_hi:[1,0]
	v_pk_mul_f32 v[32:33], v[230:231], v[32:33]
	v_pk_mul_f32 v[34:35], v[232:233], v[34:35]
	s_waitcnt vmcnt(27)
	v_pk_fma_f32 v[28:29], v[76:77], v[32:33], v[28:29]
	v_pk_fma_f32 v[30:31], v[78:79], v[34:35], v[30:31]
	global_store_dwordx4 v160, v[28:31], s[64:65] offset:3072 nt
	v_pk_mul_f32 v[166:167], v[16:17], v[16:17]
	v_pk_mul_f32 v[168:169], v[18:19], v[18:19]
	v_pk_fma_f32 v[166:167], v[20:21], v[20:21], v[166:167]
	v_pk_fma_f32 v[168:169], v[22:23], v[22:23], v[168:169]
	v_pk_fma_f32 v[166:167], v[24:25], v[24:25], v[166:167]
	v_pk_fma_f32 v[168:169], v[26:27], v[26:27], v[168:169]
	v_pk_fma_f32 v[166:167], v[28:29], v[28:29], v[166:167]
	v_pk_fma_f32 v[168:169], v[30:31], v[30:31], v[168:169]
	v_pk_add_f32 v[166:167], v[166:167], v[168:169]
	s_nop 0
	v_add_f32_e32 v164, v166, v167
	v_mov_b32_e32 v165, v164
	s_nop 1
	v_permlane32_swap_b32_e32 v165, v164
	v_add_f32_e32 v164, v164, v165
	v_mov_b32_e32 v165, v164
	s_nop 1
	v_permlane16_swap_b32_e32 v165, v164
	v_add_f32_e32 v164, v164, v165
	s_nop 1
	v_add_f32_dpp v164, v164, v164 row_ror:8 row_mask:0xf bank_mask:0xf
	s_nop 1
	v_add_f32_dpp v164, v164, v164 row_ror:4 row_mask:0xf bank_mask:0xf
	s_nop 1
	v_add_f32_dpp v164, v164, v164 row_ror:2 row_mask:0xf bank_mask:0xf
	s_nop 1
	v_add_f32_dpp v164, v164, v164 row_ror:1 row_mask:0xf bank_mask:0xf
	s_nop 0
	v_fmamk_f32 v164, v164, 0x3a800000, v200
	v_rsq_f32_e32 v164, v164
	s_nop 0
	v_pk_mul_f32 v[16:17], v[16:17], v[164:165] op_sel_hi:[1,0]
	v_pk_mul_f32 v[18:19], v[18:19], v[164:165] op_sel_hi:[1,0]
	v_pk_mul_f32 v[16:17], v[234:235], v[16:17]
	v_pk_mul_f32 v[18:19], v[236:237], v[18:19]
	s_waitcnt vmcnt(15)
	v_pk_fma_f32 v[16:17], v[172:173], v[16:17], v[80:81]
	v_pk_fma_f32 v[18:19], v[174:175], v[18:19], v[82:83]
	v_cvt_pk_bf16_f32 v16, v16, v17
	v_cvt_pk_bf16_f32 v17, v18, v19
	global_store_dwordx2 v[252:253], v[16:17], off
	v_pk_mul_f32 v[20:21], v[20:21], v[164:165] op_sel_hi:[1,0]
	v_pk_mul_f32 v[22:23], v[22:23], v[164:165] op_sel_hi:[1,0]
	v_pk_mul_f32 v[20:21], v[238:239], v[20:21]
	v_pk_mul_f32 v[22:23], v[240:241], v[22:23]
	s_waitcnt vmcnt(15)
	v_pk_fma_f32 v[20:21], v[176:177], v[20:21], v[84:85]
	v_pk_fma_f32 v[22:23], v[178:179], v[22:23], v[86:87]
	v_cvt_pk_bf16_f32 v20, v20, v21
	v_cvt_pk_bf16_f32 v21, v22, v23
	global_store_dwordx2 v[252:253], v[20:21], off offset:512
	v_pk_mul_f32 v[24:25], v[24:25], v[164:165] op_sel_hi:[1,0]
	v_pk_mul_f32 v[26:27], v[26:27], v[164:165] op_sel_hi:[1,0]
	v_pk_mul_f32 v[24:25], v[242:243], v[24:25]
	v_pk_mul_f32 v[26:27], v[244:245], v[26:27]
	s_waitcnt vmcnt(15)
	v_pk_fma_f32 v[24:25], v[180:181], v[24:25], v[88:89]
	v_pk_fma_f32 v[26:27], v[182:183], v[26:27], v[90:91]
	v_cvt_pk_bf16_f32 v24, v24, v25
	v_cvt_pk_bf16_f32 v25, v26, v27
	global_store_dwordx2 v[252:253], v[24:25], off offset:1024
	v_pk_mul_f32 v[28:29], v[28:29], v[164:165] op_sel_hi:[1,0]
	v_pk_mul_f32 v[30:31], v[30:31], v[164:165] op_sel_hi:[1,0]
	v_pk_mul_f32 v[28:29], v[246:247], v[28:29]
	v_pk_mul_f32 v[30:31], v[248:249], v[30:31]
	s_waitcnt vmcnt(15)
	v_pk_fma_f32 v[28:29], v[184:185], v[28:29], v[92:93]
	v_pk_fma_f32 v[30:31], v[186:187], v[30:31], v[94:95]
	v_cvt_pk_bf16_f32 v28, v28, v29
	v_cvt_pk_bf16_f32 v29, v30, v31
	global_store_dwordx2 v[252:253], v[28:29], off offset:1536
	s_branch .LBB0_131

; __device__ __forceinline__ float bflo(unsigned w) { return __uint_as_float(w << 16); }
; __device__ __forceinline__ float bfhi(unsigned w) { return __uint_as_float(w & 0xffff0000u); }
; __device__ __forceinline__ void row_pass(const RowPass& R, int gw, int ngw, int lane) {
;     ...
;     for (int row0 = gw; row0 < M; row0 += NR * ngw) {
;         f32x4 v[NR][4]; u32x2 yw[NR][4]; bool act[NR]; float* xrow[NR]; int bbs[NR];
; #pragma unroll
;         for (int k = 0; k < NR; ++k) {
;             const int row = row0 + k * ngw;
;             const int rowc = row < M ? row : row0;
;             const int b = rowc / RPB, i = rowc - b * RPB; const bool isctx = i < CTXL;
;             act[k] = (row < M) && !(isctx && R.skip_ctx);
;             bbs[k] = isctx ? 8 : b;
;             xrow[k] = isctx ? R.xc + ((size_t)b * CTXL + i) * DM : R.out + ((size_t)b * SEQ + (i - CTXL)) * DM;
;             const float* src = R.init ? (isctx ? R.ctx_in + ((size_t)b * CTXL + i) * DM : R.x_in + ((size_t)b * SEQ + (i - CTXL)) * DM) : xrow[k];
;             if (act[k]) {
; #pragma unroll
;                 for (int j = 0; j < 4; ++j) v[k][j] = __builtin_nontemporal_load((const f32x4*)(src + lane * 4 + 256 * j));
;                 if (R.update) { const bf16* yr = R.Y + (size_t)rowc * DM;
; #pragma unroll
;                     for (int j = 0; j < 4; ++j) yw[k][j] = __builtin_nontemporal_load((const u32x2*)(yr + lane * 4 + 256 * j)); }
;             }
;         }
; #pragma unroll
;         for (int k = 0; k < NR; ++k) {
;             if (!act[k]) continue;
;             const int row = row0 + k * ngw, bb = bbs[k];
;             if (R.update) {
;                 f32x4 y[4]; float ss = 0.f;
; #pragma unroll
;                 for (int j = 0; j < 4; ++j) { const u32x2 w = yw[k][j]; y[j] = (f32x4){bflo(w.x), bfhi(w.x), bflo(w.y), bfhi(w.y)};
;                     ss += (y[j][0] * y[j][0] + y[j][1] * y[j][1]) + (y[j][2] * y[j][2] + y[j][3] * y[j][3]); }
;                 const float rstd = __builtin_amdgcn_rsqf(wave_sum(ss) * (1.0f / DM) + EPS);
;                 const float* gate = R.mod + ((size_t)(R.lg * 9 + bb) * NMOD + R.gi) * DM;
; #pragma unroll
;                 for (int j = 0; j < 4; ++j) { const f32x4 g = *(const f32x4*)(gate + lane * 4 + 256 * j), gp = *(const f32x4*)(R.gpost + lane * 4 + 256 * j);
;                     v[k][j] = v[k][j] + g * (y[j] * rstd * gp); }
.LBB0_149:
	s_mul_hi_i32 s6, s19, 0x78787879
	s_lshr_b32 s7, s6, 31
	s_ashr_i32 s6, s6, 11
	s_add_i32 s6, s6, s7
	s_mul_i32 s7, s6, 0xffffef00
	s_add_i32 s7, s19, s7
	s_cmpk_gt_i32 s7, 0xff
	s_cselect_b64 s[50:51], -1, 0
	s_add_i32 s8, s44, s19
	s_cmp_lt_i32 s8, 0x8800
	s_cbranch_scc0 .Lr3_slow
	s_mul_hi_i32 s9, s8, 0x78787879
	s_lshr_b32 s25, s9, 31
	s_ashr_i32 s9, s9, 11
	s_add_i32 s9, s9, s25
	s_mul_i32 s25, s9, 0xffffef00
	s_add_i32 s25, s8, s25
	s_cmpk_gt_i32 s25, 0xff
	s_cselect_b64 s[52:53], -1, 0
	s_cmp_lg_u64 s[4:5], 0
	s_cbranch_scc0 .Lr3_slow_u
	v_lshlrev_b32_e32 v160, 2, v36
	s_cmp_lg_u32 s6, s9
	s_cbranch_scc1 .Lr3_slow_diff
	s_cmp_eq_u32 s50, s52
	s_cbranch_scc1 .Lr3_slow_same
.Lr3_slow_diff:
	s_add_i32 s72, s7, 0xffffff00
	s_cmp_lg_u64 s[50:51], 0
	s_cselect_b32 s27, s22, s49
	s_cselect_b32 s32, s23, s55
	s_cselect_b32 s37, 24, 20
	s_cselect_b32 s72, s72, s7
	s_cselect_b32 s85, s6, 8
	s_mov_b32 s40, s6
	s_mov_b32 s41, 0
	s_lshl_b64 s[40:41], s[40:41], s37
	s_add_u32 s40, s27, s40
	s_addc_u32 s41, s32, s41
	s_lshl_b32 s72, s72, 12
	s_add_u32 s40, s40, s72
	s_addc_u32 s41, s41, 0
	s_add_i32 s27, s85, s3
	s_mul_hi_i32 s32, s27, 0x6000
	s_mulk_i32 s27, 0x6000
	s_add_u32 s66, s34, s27
	s_addc_u32 s67, s35, s32
	s_add_u32 s66, s66, 0x5000
	s_addc_u32 s67, s67, 0
	s_add_i32 s27, s85, s13
	s_mul_hi_i32 s32, s27, 0x6000
	s_mulk_i32 s27, 0x6000
	s_add_u32 s38, s34, s27
	s_addc_u32 s39, s35, s32
	s_add_u32 s46, s38, 0x1000
	s_addc_u32 s47, s39, 0
	global_load_dwordx4 v[12:15], v160, s[40:41] nt
	global_load_dwordx4 v[8:11], v160, s[40:41] offset:1024 nt
	global_load_dwordx4 v[4:7], v160, s[40:41] offset:2048 nt
	global_load_dwordx4 v[0:3], v160, s[40:41] offset:3072 nt
	global_load_dwordx2 v[54:55], v[46:47], off offset:-1536 nt
	global_load_dwordx2 v[52:53], v[46:47], off offset:-1024 nt
	global_load_dwordx2 v[50:51], v[46:47], off offset:-512 nt
	global_load_dwordx2 v[48:49], v[46:47], off nt
	global_load_dwordx4 v[64:67], v160, s[66:67]
	global_load_dwordx4 v[68:71], v160, s[66:67] offset:1024
	global_load_dwordx4 v[72:75], v160, s[66:67] offset:2048
	global_load_dwordx4 v[76:79], v160, s[66:67] offset:3072
	s_mov_b32 s6, s8
	s_ashr_i32 s7, s8, 31
	s_lshl_b64 s[6:7], s[6:7], 11
	v_lshl_add_u64 v[250:251], v[38:39], 0, s[6:7]
	v_lshl_add_u64 v[252:253], v[40:41], 0, s[6:7]
	s_mov_b64 s[6:7], s[52:53]
	s_add_i32 s72, s25, 0xffffff00
	s_cmp_lg_u64 s[6:7], 0
	s_cselect_b32 s27, s22, s49
	s_cselect_b32 s32, s23, s55
	s_cselect_b32 s37, 24, 20
	s_cselect_b32 s72, s72, s25
	s_cselect_b32 s85, s9, 8
	s_mov_b32 s64, s9
	s_mov_b32 s65, 0
	s_lshl_b64 s[64:65], s[64:65], s37
	s_add_u32 s64, s27, s64
	s_addc_u32 s65, s32, s65
	s_lshl_b32 s72, s72, 12
	s_add_u32 s64, s64, s72
	s_addc_u32 s65, s65, 0
	s_add_i32 s27, s85, s3
	s_mul_hi_i32 s32, s27, 0x6000
	s_mulk_i32 s27, 0x6000
	s_add_u32 s10, s34, s27
	s_addc_u32 s11, s35, s32
	s_add_u32 s10, s10, 0x5000
	s_addc_u32 s11, s11, 0
	s_add_i32 s27, s85, s13
	s_mul_hi_i32 s32, s27, 0x6000
	s_mulk_i32 s27, 0x6000
	s_add_u32 s50, s34, s27
	s_addc_u32 s51, s35, s32
	s_add_u32 s52, s50, 0x1000
	s_addc_u32 s53, s51, 0
	global_load_dwordx4 v[16:19], v160, s[64:65] nt
	global_load_dwordx4 v[20:23], v160, s[64:65] offset:1024 nt
	global_load_dwordx4 v[24:27], v160, s[64:65] offset:2048 nt
	global_load_dwordx4 v[28:31], v160, s[64:65] offset:3072 nt
	global_load_dwordx2 v[62:63], v[250:251], off nt
	global_load_dwordx2 v[60:61], v[250:251], off offset:512 nt
	global_load_dwordx2 v[58:59], v[250:251], off offset:1024 nt
	global_load_dwordx2 v[56:57], v[250:251], off offset:1536 nt
	global_load_dwordx4 v[80:83], v160, s[38:39]
	global_load_dwordx4 v[84:87], v160, s[38:39] offset:1024
	global_load_dwordx4 v[88:91], v160, s[38:39] offset:2048
	global_load_dwordx4 v[92:95], v160, s[38:39] offset:3072
	global_load_dwordx4 v[172:175], v160, s[46:47]
	global_load_dwordx4 v[176:179], v160, s[46:47] offset:1024
	global_load_dwordx4 v[180:183], v160, s[46:47] offset:2048
	global_load_dwordx4 v[184:187], v160, s[46:47] offset:3072
	global_load_dwordx4 v[188:191], v160, s[10:11]
	global_load_dwordx4 v[192:195], v160, s[10:11] offset:1024
	global_load_dwordx4 v[196:199], v160, s[10:11] offset:2048
	global_load_dwordx4 v[96:99], v160, s[10:11] offset:3072
	s_waitcnt vmcnt(24)
	v_lshlrev_b32_e32 v32, 16, v54
	v_and_b32_e32 v33, 0xffff0000, v54
	v_lshlrev_b32_e32 v34, 16, v55
	v_and_b32_e32 v35, 0xffff0000, v55
	v_pk_mul_f32 v[166:167], v[32:33], v[32:33]
	v_pk_mul_f32 v[168:169], v[34:35], v[34:35]
	v_lshlrev_b32_e32 v32, 16, v52
	v_and_b32_e32 v33, 0xffff0000, v52
	v_lshlrev_b32_e32 v34, 16, v53
	v_and_b32_e32 v35, 0xffff0000, v53
	v_pk_fma_f32 v[166:167], v[32:33], v[32:33], v[166:167]
	v_pk_fma_f32 v[168:169], v[34:35], v[34:35], v[168:169]
	v_lshlrev_b32_e32 v32, 16, v50
	v_and_b32_e32 v33, 0xffff0000, v50
	v_lshlrev_b32_e32 v34, 16, v51
	v_and_b32_e32 v35, 0xffff0000, v51
	v_pk_fma_f32 v[166:167], v[32:33], v[32:33], v[166:167]
	v_pk_fma_f32 v[168:169], v[34:35], v[34:35], v[168:169]
	v_lshlrev_b32_e32 v32, 16, v48
	v_and_b32_e32 v33, 0xffff0000, v48
	v_lshlrev_b32_e32 v34, 16, v49
	v_and_b32_e32 v35, 0xffff0000, v49
	v_pk_fma_f32 v[166:167], v[32:33], v[32:33], v[166:167]
	v_pk_fma_f32 v[168:169], v[34:35], v[34:35], v[168:169]
	v_pk_add_f32 v[166:167], v[166:167], v[168:169]
	s_nop 0
	v_add_f32_e32 v164, v166, v167
	v_mov_b32_e32 v165, v164
	s_nop 1
	v_permlane32_swap_b32_e32 v165, v164
	v_add_f32_e32 v164, v164, v165
	v_mov_b32_e32 v165, v164
	s_nop 1
	v_permlane16_swap_b32_e32 v165, v164
	v_add_f32_e32 v164, v164, v165
	s_nop 1
	v_add_f32_dpp v164, v164, v164 row_ror:8 row_mask:0xf bank_mask:0xf
	s_nop 1
	v_add_f32_dpp v164, v164, v164 row_ror:4 row_mask:0xf bank_mask:0xf
	s_nop 1
	v_add_f32_dpp v164, v164, v164 row_ror:2 row_mask:0xf bank_mask:0xf
	s_nop 1
	v_add_f32_dpp v164, v164, v164 row_ror:1 row_mask:0xf bank_mask:0xf
	s_nop 0
	v_fmamk_f32 v164, v164, 0x3a800000, v200
	v_rsq_f32_e32 v164, v164
	v_lshlrev_b32_e32 v32, 16, v54
	v_and_b32_e32 v33, 0xffff0000, v54
	v_lshlrev_b32_e32 v34, 16, v55
	v_and_b32_e32 v35, 0xffff0000, v55
	v_pk_mul_f32 v[32:33], v[32:33], v[164:165] op_sel_hi:[1,0]
	v_pk_mul_f32 v[34:35], v[34:35], v[164:165] op_sel_hi:[1,0]
	v_pk_mul_f32 v[32:33], v[218:219], v[32:33]
	v_pk_mul_f32 v[34:35], v[220:221], v[34:35]
	s_waitcnt vmcnt(23)
; __device__ __forceinline__ unsigned pk2(float lo, float hi) { return pg8::cvt_pk_bf16(lo, hi); }
;     __device__ __forceinline__ void init(int N, int G, int c, int latent_only) { lat = latent_only; b.init(latent_only ? NB * SEQ : M, N, G, c); }
;     __device__ __forceinline__ void init(int c_, unsigned* cnt_) { lat.init(NB * SEQ, FF2, 1, 0); c = c_; cnt = cnt_; }
; __device__ __forceinline__ void row_pass(const RowPass& R, int gw, int ngw, int lane) {
;     ...
;                 for (int j = 0; j < 4; ++j) { const f32x4 g = *(const f32x4*)(gate + lane * 4 + 256 * j), gp = *(const f32x4*)(R.gpost + lane * 4 + 256 * j);
;                     v[k][j] = v[k][j] + g * (y[j] * rstd * gp); }
;             }
;             if (R.init || R.update) {
; #pragma unroll
;                 for (int j = 0; j < 4; ++j) __builtin_nontemporal_store(v[k][j], (f32x4*)(xrow[k] + lane * 4 + 256 * j));
;             }
;             if (R.norm_out) {
;                 float ss = 0.f;
; #pragma unroll
;                 for (int j = 0; j < 4; ++j) ss += (v[k][j][0] * v[k][j][0] + v[k][j][1] * v[k][j][1]) + (v[k][j][2] * v[k][j][2] + v[k][j][3] * v[k][j][3]);
;                 const float rstd = __builtin_amdgcn_rsqf(wave_sum(ss) * (1.0f / DM) + EPS);
;                 const float* shift = R.mod + ((size_t)(R.ln * 9 + bb) * NMOD + R.si) * DM; const float* scale = shift + DM;
;                 bf16* hr = R.H + (size_t)row * DM;
; #pragma unroll
;                 for (int j = 0; j < 4; ++j) { const f32x4 gp = *(const f32x4*)(R.gpre + lane * 4 + 256 * j), sh = *(const f32x4*)(shift + lane * 4 + 256 * j), sc = *(const f32x4*)(scale + lane * 4 + 256 * j);
;                     const f32x4 hv = (v[k][j] * rstd * gp) * (sc + 1.0f) + sh;
;                     u32x2 w; w.x = pk2(hv[0], hv[1]); w.y = pk2(hv[2], hv[3]); *(u32x2*)(hr + lane * 4 + 256 * j) = w; }
	v_pk_fma_f32 v[12:13], v[64:65], v[32:33], v[12:13]
	v_pk_fma_f32 v[14:15], v[66:67], v[34:35], v[14:15]
	global_store_dwordx4 v160, v[12:15], s[40:41] nt
	v_lshlrev_b32_e32 v32, 16, v52
	v_and_b32_e32 v33, 0xffff0000, v52
	v_lshlrev_b32_e32 v34, 16, v53
	v_and_b32_e32 v35, 0xffff0000, v53
	v_pk_mul_f32 v[32:33], v[32:33], v[164:165] op_sel_hi:[1,0]
	v_pk_mul_f32 v[34:35], v[34:35], v[164:165] op_sel_hi:[1,0]
	v_pk_mul_f32 v[32:33], v[222:223], v[32:33]
	v_pk_mul_f32 v[34:35], v[224:225], v[34:35]
	s_waitcnt vmcnt(23)
	v_pk_fma_f32 v[8:9], v[68:69], v[32:33], v[8:9]
	v_pk_fma_f32 v[10:11], v[70:71], v[34:35], v[10:11]
	global_store_dwordx4 v160, v[8:11], s[40:41] offset:1024 nt
	v_lshlrev_b32_e32 v32, 16, v50
	v_and_b32_e32 v33, 0xffff0000, v50
	v_lshlrev_b32_e32 v34, 16, v51
	v_and_b32_e32 v35, 0xffff0000, v51
	v_pk_mul_f32 v[32:33], v[32:33], v[164:165] op_sel_hi:[1,0]
	v_pk_mul_f32 v[34:35], v[34:35], v[164:165] op_sel_hi:[1,0]
	v_pk_mul_f32 v[32:33], v[226:227], v[32:33]
	v_pk_mul_f32 v[34:35], v[228:229], v[34:35]
	s_waitcnt vmcnt(23)
	v_pk_fma_f32 v[4:5], v[72:73], v[32:33], v[4:5]
	v_pk_fma_f32 v[6:7], v[74:75], v[34:35], v[6:7]
	global_store_dwordx4 v160, v[4:7], s[40:41] offset:2048 nt
	v_lshlrev_b32_e32 v32, 16, v48
	v_and_b32_e32 v33, 0xffff0000, v48
	v_lshlrev_b32_e32 v34, 16, v49
	v_and_b32_e32 v35, 0xffff0000, v49
	v_pk_mul_f32 v[32:33], v[32:33], v[164:165] op_sel_hi:[1,0]
	v_pk_mul_f32 v[34:35], v[34:35], v[164:165] op_sel_hi:[1,0]
	v_pk_mul_f32 v[32:33], v[230:231], v[32:33]
	v_pk_mul_f32 v[34:35], v[232:233], v[34:35]
	s_waitcnt vmcnt(23)
	v_pk_fma_f32 v[0:1], v[76:77], v[32:33], v[0:1]
	v_pk_fma_f32 v[2:3], v[78:79], v[34:35], v[2:3]
	global_store_dwordx4 v160, v[0:3], s[40:41] offset:3072 nt
	global_load_dwordx4 v[64:67], v160, s[50:51]
	global_load_dwordx4 v[68:71], v160, s[50:51] offset:1024
	global_load_dwordx4 v[72:75], v160, s[50:51] offset:2048
	global_load_dwordx4 v[76:79], v160, s[50:51] offset:3072
	v_add_co_u32_e32 v250, vcc, 0xfbc00000, v46
	v_addc_co_u32_e32 v251, vcc, -1, v47, vcc
	v_pk_mul_f32 v[166:167], v[12:13], v[12:13]
	v_pk_mul_f32 v[168:169], v[14:15], v[14:15]
	v_pk_fma_f32 v[166:167], v[8:9], v[8:9], v[166:167]
	v_pk_fma_f32 v[168:169], v[10:11], v[10:11], v[168:169]
	v_pk_fma_f32 v[166:167], v[4:5], v[4:5], v[166:167]
	v_pk_fma_f32 v[168:169], v[6:7], v[6:7], v[168:169]
	v_pk_fma_f32 v[166:167], v[0:1], v[0:1], v[166:167]
	v_pk_fma_f32 v[168:169], v[2:3], v[2:3], v[168:169]
	v_pk_add_f32 v[166:167], v[166:167], v[168:169]
	s_nop 0
	v_add_f32_e32 v164, v166, v167
	v_mov_b32_e32 v165, v164
	s_nop 1
	v_permlane32_swap_b32_e32 v165, v164
	v_add_f32_e32 v164, v164, v165
	v_mov_b32_e32 v165, v164
	s_nop 1
	v_permlane16_swap_b32_e32 v165, v164
	v_add_f32_e32 v164, v164, v165
	s_nop 1
	v_add_f32_dpp v164, v164, v164 row_ror:8 row_mask:0xf bank_mask:0xf
	s_nop 1
	v_add_f32_dpp v164, v164, v164 row_ror:4 row_mask:0xf bank_mask:0xf
	s_nop 1
	v_add_f32_dpp v164, v164, v164 row_ror:2 row_mask:0xf bank_mask:0xf
	s_nop 1
	v_add_f32_dpp v164, v164, v164 row_ror:1 row_mask:0xf bank_mask:0xf
	s_nop 0
	v_fmamk_f32 v164, v164, 0x3a800000, v200
	v_rsq_f32_e32 v164, v164
	s_nop 0
	v_pk_mul_f32 v[12:13], v[12:13], v[164:165] op_sel_hi:[1,0]
	v_pk_mul_f32 v[14:15], v[14:15], v[164:165] op_sel_hi:[1,0]
	v_pk_mul_f32 v[12:13], v[234:235], v[12:13]
	v_pk_mul_f32 v[14:15], v[236:237], v[14:15]
	s_waitcnt vmcnt(15)
	v_pk_add_f32 v[172:173], v[172:173], 1.0 op_sel_hi:[1,0]
	v_pk_add_f32 v[174:175], v[174:175], 1.0 op_sel_hi:[1,0]
	v_pk_fma_f32 v[12:13], v[172:173], v[12:13], v[80:81]
	v_pk_fma_f32 v[14:15], v[174:175], v[14:15], v[82:83]
	v_cvt_pk_bf16_f32 v12, v12, v13
	v_cvt_pk_bf16_f32 v13, v14, v15
	global_store_dwordx2 v[250:251], v[12:13], off offset:-1536
	global_load_dwordx4 v[80:83], v160, s[52:53]
	v_pk_mul_f32 v[8:9], v[8:9], v[164:165] op_sel_hi:[1,0]
	v_pk_mul_f32 v[10:11], v[10:11], v[164:165] op_sel_hi:[1,0]
	v_pk_mul_f32 v[8:9], v[238:239], v[8:9]
	v_pk_mul_f32 v[10:11], v[240:241], v[10:11]
	s_waitcnt vmcnt(16)
	v_pk_add_f32 v[176:177], v[176:177], 1.0 op_sel_hi:[1,0]
	v_pk_add_f32 v[178:179], v[178:179], 1.0 op_sel_hi:[1,0]
	v_pk_fma_f32 v[8:9], v[176:177], v[8:9], v[84:85]
	v_pk_fma_f32 v[10:11], v[178:179], v[10:11], v[86:87]
	v_cvt_pk_bf16_f32 v8, v8, v9
	v_cvt_pk_bf16_f32 v9, v10, v11
	global_store_dwordx2 v[250:251], v[8:9], off offset:-1024
	global_load_dwordx4 v[84:87], v160, s[52:53] offset:1024
	v_pk_mul_f32 v[4:5], v[4:5], v[164:165] op_sel_hi:[1,0]
	v_pk_mul_f32 v[6:7], v[6:7], v[164:165] op_sel_hi:[1,0]
	v_pk_mul_f32 v[4:5], v[242:243], v[4:5]
	v_pk_mul_f32 v[6:7], v[244:245], v[6:7]
	s_waitcnt vmcnt(17)
	v_pk_add_f32 v[180:181], v[180:181], 1.0 op_sel_hi:[1,0]
	v_pk_add_f32 v[182:183], v[182:183], 1.0 op_sel_hi:[1,0]
	v_pk_fma_f32 v[4:5], v[180:181], v[4:5], v[88:89]
	v_pk_fma_f32 v[6:7], v[182:183], v[6:7], v[90:91]
	v_cvt_pk_bf16_f32 v4, v4, v5
	v_cvt_pk_bf16_f32 v5, v6, v7
	global_store_dwordx2 v[250:251], v[4:5], off offset:-512
	global_load_dwordx4 v[88:91], v160, s[52:53] offset:2048
	v_pk_mul_f32 v[0:1], v[0:1], v[164:165] op_sel_hi:[1,0]
	v_pk_mul_f32 v[2:3], v[2:3], v[164:165] op_sel_hi:[1,0]
	v_pk_mul_f32 v[0:1], v[246:247], v[0:1]
	v_pk_mul_f32 v[2:3], v[248:249], v[2:3]
	s_waitcnt vmcnt(18)
	v_pk_add_f32 v[184:185], v[184:185], 1.0 op_sel_hi:[1,0]
	v_pk_add_f32 v[186:187], v[186:187], 1.0 op_sel_hi:[1,0]
	v_pk_fma_f32 v[0:1], v[184:185], v[0:1], v[92:93]
	v_pk_fma_f32 v[2:3], v[186:187], v[2:3], v[94:95]
	v_cvt_pk_bf16_f32 v0, v0, v1
	v_cvt_pk_bf16_f32 v1, v2, v3
	global_store_dwordx2 v[250:251], v[0:1], off
	global_load_dwordx4 v[92:95], v160, s[52:53] offset:3072
	s_waitcnt vmcnt(28)
; __device__ __forceinline__ unsigned pk2(float lo, float hi) { return pg8::cvt_pk_bf16(lo, hi); }
; __device__ __forceinline__ float bflo(unsigned w) { return __uint_as_float(w << 16); }
; __device__ __forceinline__ float bfhi(unsigned w) { return __uint_as_float(w & 0xffff0000u); }
; __device__ __forceinline__ void row_pass(const RowPass& R, int gw, int ngw, int lane) {
;     ...
;             if (R.update) {
;                 f32x4 y[4]; float ss = 0.f;
; #pragma unroll
;                 for (int j = 0; j < 4; ++j) { const u32x2 w = yw[k][j]; y[j] = (f32x4){bflo(w.x), bfhi(w.x), bflo(w.y), bfhi(w.y)};
;                     ss += (y[j][0] * y[j][0] + y[j][1] * y[j][1]) + (y[j][2] * y[j][2] + y[j][3] * y[j][3]); }
;                 const float rstd = __builtin_amdgcn_rsqf(wave_sum(ss) * (1.0f / DM) + EPS);
;                 const float* gate = R.mod + ((size_t)(R.lg * 9 + bb) * NMOD + R.gi) * DM;
; #pragma unroll
;                 for (int j = 0; j < 4; ++j) { const f32x4 g = *(const f32x4*)(gate + lane * 4 + 256 * j), gp = *(const f32x4*)(R.gpost + lane * 4 + 256 * j);
;                     v[k][j] = v[k][j] + g * (y[j] * rstd * gp); }
;             }
;             if (R.init || R.update) {
; #pragma unroll
;                 for (int j = 0; j < 4; ++j) __builtin_nontemporal_store(v[k][j], (f32x4*)(xrow[k] + lane * 4 + 256 * j));
;             }
;             if (R.norm_out) {
;                 float ss = 0.f;
; #pragma unroll
;                 for (int j = 0; j < 4; ++j) ss += (v[k][j][0] * v[k][j][0] + v[k][j][1] * v[k][j][1]) + (v[k][j][2] * v[k][j][2] + v[k][j][3] * v[k][j][3]);
;                 const float rstd = __builtin_amdgcn_rsqf(wave_sum(ss) * (1.0f / DM) + EPS);
;                 const float* shift = R.mod + ((size_t)(R.ln * 9 + bb) * NMOD + R.si) * DM; const float* scale = shift + DM;
;                 bf16* hr = R.H + (size_t)row * DM;
; #pragma unroll
;                 for (int j = 0; j < 4; ++j) { const f32x4 gp = *(const f32x4*)(R.gpre + lane * 4 + 256 * j), sh = *(const f32x4*)(shift + lane * 4 + 256 * j), sc = *(const f32x4*)(scale + lane * 4 + 256 * j);
;                     const f32x4 hv = (v[k][j] * rstd * gp) * (sc + 1.0f) + sh;
;                     u32x2 w; w.x = pk2(hv[0], hv[1]); w.y = pk2(hv[2], hv[3]); *(u32x2*)(hr + lane * 4 + 256 * j) = w; }
	v_lshlrev_b32_e32 v32, 16, v62
	v_and_b32_e32 v33, 0xffff0000, v62
	v_lshlrev_b32_e32 v34, 16, v63
	v_and_b32_e32 v35, 0xffff0000, v63
	v_pk_mul_f32 v[166:167], v[32:33], v[32:33]
	v_pk_mul_f32 v[168:169], v[34:35], v[34:35]
	v_lshlrev_b32_e32 v32, 16, v60
	v_and_b32_e32 v33, 0xffff0000, v60
	v_lshlrev_b32_e32 v34, 16, v61
	v_and_b32_e32 v35, 0xffff0000, v61
	v_pk_fma_f32 v[166:167], v[32:33], v[32:33], v[166:167]
	v_pk_fma_f32 v[168:169], v[34:35], v[34:35], v[168:169]
	v_lshlrev_b32_e32 v32, 16, v58
	v_and_b32_e32 v33, 0xffff0000, v58
	v_lshlrev_b32_e32 v34, 16, v59
	v_and_b32_e32 v35, 0xffff0000, v59
	v_pk_fma_f32 v[166:167], v[32:33], v[32:33], v[166:167]
	v_pk_fma_f32 v[168:169], v[34:35], v[34:35], v[168:169]
	v_lshlrev_b32_e32 v32, 16, v56
	v_and_b32_e32 v33, 0xffff0000, v56
	v_lshlrev_b32_e32 v34, 16, v57
	v_and_b32_e32 v35, 0xffff0000, v57
	v_pk_fma_f32 v[166:167], v[32:33], v[32:33], v[166:167]
	v_pk_fma_f32 v[168:169], v[34:35], v[34:35], v[168:169]
	v_pk_add_f32 v[166:167], v[166:167], v[168:169]
	s_nop 0
	v_add_f32_e32 v164, v166, v167
	v_mov_b32_e32 v165, v164
	s_nop 1
	v_permlane32_swap_b32_e32 v165, v164
	v_add_f32_e32 v164, v164, v165
	v_mov_b32_e32 v165, v164
	s_nop 1
	v_permlane16_swap_b32_e32 v165, v164
	v_add_f32_e32 v164, v164, v165
	s_nop 1
	v_add_f32_dpp v164, v164, v164 row_ror:8 row_mask:0xf bank_mask:0xf
	s_nop 1
	v_add_f32_dpp v164, v164, v164 row_ror:4 row_mask:0xf bank_mask:0xf
	s_nop 1
	v_add_f32_dpp v164, v164, v164 row_ror:2 row_mask:0xf bank_mask:0xf
	s_nop 1
	v_add_f32_dpp v164, v164, v164 row_ror:1 row_mask:0xf bank_mask:0xf
	s_nop 0
	v_fmamk_f32 v164, v164, 0x3a800000, v200
	v_rsq_f32_e32 v164, v164
	v_lshlrev_b32_e32 v32, 16, v62
	v_and_b32_e32 v33, 0xffff0000, v62
	v_lshlrev_b32_e32 v34, 16, v63
	v_and_b32_e32 v35, 0xffff0000, v63
	v_pk_mul_f32 v[32:33], v[32:33], v[164:165] op_sel_hi:[1,0]
	v_pk_mul_f32 v[34:35], v[34:35], v[164:165] op_sel_hi:[1,0]
	v_pk_mul_f32 v[32:33], v[218:219], v[32:33]
	v_pk_mul_f32 v[34:35], v[220:221], v[34:35]
	s_waitcnt vmcnt(19)
	v_pk_fma_f32 v[16:17], v[188:189], v[32:33], v[16:17]
	v_pk_fma_f32 v[18:19], v[190:191], v[34:35], v[18:19]
	global_store_dwordx4 v160, v[16:19], s[64:65] nt
	v_lshlrev_b32_e32 v32, 16, v60
	v_and_b32_e32 v33, 0xffff0000, v60
	v_lshlrev_b32_e32 v34, 16, v61
	v_and_b32_e32 v35, 0xffff0000, v61
	v_pk_mul_f32 v[32:33], v[32:33], v[164:165] op_sel_hi:[1,0]
	v_pk_mul_f32 v[34:35], v[34:35], v[164:165] op_sel_hi:[1,0]
	v_pk_mul_f32 v[32:33], v[222:223], v[32:33]
	v_pk_mul_f32 v[34:35], v[224:225], v[34:35]
	s_waitcnt vmcnt(19)
	v_pk_fma_f32 v[20:21], v[192:193], v[32:33], v[20:21]
	v_pk_fma_f32 v[22:23], v[194:195], v[34:35], v[22:23]
	global_store_dwordx4 v160, v[20:23], s[64:65] offset:1024 nt
	v_lshlrev_b32_e32 v32, 16, v58
	v_and_b32_e32 v33, 0xffff0000, v58
	v_lshlrev_b32_e32 v34, 16, v59
	v_and_b32_e32 v35, 0xffff0000, v59
	v_pk_mul_f32 v[32:33], v[32:33], v[164:165] op_sel_hi:[1,0]
	v_pk_mul_f32 v[34:35], v[34:35], v[164:165] op_sel_hi:[1,0]
	v_pk_mul_f32 v[32:33], v[226:227], v[32:33]
	v_pk_mul_f32 v[34:35], v[228:229], v[34:35]
	s_waitcnt vmcnt(19)
	v_pk_fma_f32 v[24:25], v[196:197], v[32:33], v[24:25]
	v_pk_fma_f32 v[26:27], v[198:199], v[34:35], v[26:27]
	global_store_dwordx4 v160, v[24:27], s[64:65] offset:2048 nt
	v_lshlrev_b32_e32 v32, 16, v56
	v_and_b32_e32 v33, 0xffff0000, v56
	v_lshlrev_b32_e32 v34, 16, v57
	v_and_b32_e32 v35, 0xffff0000, v57
	v_pk_mul_f32 v[32:33], v[32:33], v[164:165] op_sel_hi:[1,0]
	v_pk_mul_f32 v[34:35], v[34:35], v[164:165] op_sel_hi:[1,0]
	v_pk_mul_f32 v[32:33], v[230:231], v[32:33]
	v_pk_mul_f32 v[34:35], v[232:233], v[34:35]
	s_waitcnt vmcnt(19)
	v_pk_fma_f32 v[28:29], v[96:97], v[32:33], v[28:29]
	v_pk_fma_f32 v[30:31], v[98:99], v[34:35], v[30:31]
	global_store_dwordx4 v160, v[28:31], s[64:65] offset:3072 nt
	v_pk_mul_f32 v[166:167], v[16:17], v[16:17]
	v_pk_mul_f32 v[168:169], v[18:19], v[18:19]
	v_pk_fma_f32 v[166:167], v[20:21], v[20:21], v[166:167]
	v_pk_fma_f32 v[168:169], v[22:23], v[22:23], v[168:169]
	v_pk_fma_f32 v[166:167], v[24:25], v[24:25], v[166:167]
	v_pk_fma_f32 v[168:169], v[26:27], v[26:27], v[168:169]
	v_pk_fma_f32 v[166:167], v[28:29], v[28:29], v[166:167]
	v_pk_fma_f32 v[168:169], v[30:31], v[30:31], v[168:169]
	v_pk_add_f32 v[166:167], v[166:167], v[168:169]
	s_nop 0
	v_add_f32_e32 v164, v166, v167
	v_mov_b32_e32 v165, v164
	s_nop 1
	v_permlane32_swap_b32_e32 v165, v164
	v_add_f32_e32 v164, v164, v165
	v_mov_b32_e32 v165, v164
	s_nop 1
	v_permlane16_swap_b32_e32 v165, v164
	v_add_f32_e32 v164, v164, v165
	s_nop 1
	v_add_f32_dpp v164, v164, v164 row_ror:8 row_mask:0xf bank_mask:0xf
	s_nop 1
	v_add_f32_dpp v164, v164, v164 row_ror:4 row_mask:0xf bank_mask:0xf
	s_nop 1
	v_add_f32_dpp v164, v164, v164 row_ror:2 row_mask:0xf bank_mask:0xf
	s_nop 1
	v_add_f32_dpp v164, v164, v164 row_ror:1 row_mask:0xf bank_mask:0xf
	s_nop 0
	v_fmamk_f32 v164, v164, 0x3a800000, v200
	v_rsq_f32_e32 v164, v164
	s_nop 0
	v_pk_mul_f32 v[16:17], v[16:17], v[164:165] op_sel_hi:[1,0]
	v_pk_mul_f32 v[18:19], v[18:19], v[164:165] op_sel_hi:[1,0]
	v_pk_mul_f32 v[16:17], v[234:235], v[16:17]
	v_pk_mul_f32 v[18:19], v[236:237], v[18:19]
	s_waitcnt vmcnt(10)
	v_pk_add_f32 v[80:81], v[80:81], 1.0 op_sel_hi:[1,0]
	v_pk_add_f32 v[82:83], v[82:83], 1.0 op_sel_hi:[1,0]
	v_pk_fma_f32 v[16:17], v[80:81], v[16:17], v[64:65]
	v_pk_fma_f32 v[18:19], v[82:83], v[18:19], v[66:67]
	v_cvt_pk_bf16_f32 v16, v16, v17
	v_cvt_pk_bf16_f32 v17, v18, v19
	global_store_dwordx2 v[252:253], v[16:17], off
	v_pk_mul_f32 v[20:21], v[20:21], v[164:165] op_sel_hi:[1,0]
	v_pk_mul_f32 v[22:23], v[22:23], v[164:165] op_sel_hi:[1,0]
	v_pk_mul_f32 v[20:21], v[238:239], v[20:21]
	v_pk_mul_f32 v[22:23], v[240:241], v[22:23]
	s_waitcnt vmcnt(9)
; __device__ __forceinline__ unsigned pk2(float lo, float hi) { return pg8::cvt_pk_bf16(lo, hi); }
; __device__ __forceinline__ void row_pass(const RowPass& R, int gw, int ngw, int lane) {
;     ...
;     for (int row0 = gw; row0 < M; row0 += NR * ngw) {
;         f32x4 v[NR][4]; u32x2 yw[NR][4]; bool act[NR]; float* xrow[NR]; int bbs[NR];
; #pragma unroll
;         for (int k = 0; k < NR; ++k) {
;             const int row = row0 + k * ngw;
;             const int rowc = row < M ? row : row0;
;             const int b = rowc / RPB, i = rowc - b * RPB; const bool isctx = i < CTXL;
;             act[k] = (row < M) && !(isctx && R.skip_ctx);
;             bbs[k] = isctx ? 8 : b;
;             xrow[k] = isctx ? R.xc + ((size_t)b * CTXL + i) * DM : R.out + ((size_t)b * SEQ + (i - CTXL)) * DM;
;             const float* src = R.init ? (isctx ? R.ctx_in + ((size_t)b * CTXL + i) * DM : R.x_in + ((size_t)b * SEQ + (i - CTXL)) * DM) : xrow[k];
;             if (act[k]) {
; #pragma unroll
;                 for (int j = 0; j < 4; ++j) v[k][j] = __builtin_nontemporal_load((const f32x4*)(src + lane * 4 + 256 * j));
;                 if (R.update) { const bf16* yr = R.Y + (size_t)rowc * DM;
; #pragma unroll
;                     for (int j = 0; j < 4; ++j) yw[k][j] = __builtin_nontemporal_load((const u32x2*)(yr + lane * 4 + 256 * j)); }
;     ...
;             if (R.norm_out) {
;                 float ss = 0.f;
; #pragma unroll
;                 for (int j = 0; j < 4; ++j) ss += (v[k][j][0] * v[k][j][0] + v[k][j][1] * v[k][j][1]) + (v[k][j][2] * v[k][j][2] + v[k][j][3] * v[k][j][3]);
;                 const float rstd = __builtin_amdgcn_rsqf(wave_sum(ss) * (1.0f / DM) + EPS);
;                 const float* shift = R.mod + ((size_t)(R.ln * 9 + bb) * NMOD + R.si) * DM; const float* scale = shift + DM;
;                 bf16* hr = R.H + (size_t)row * DM;
; #pragma unroll
;                 for (int j = 0; j < 4; ++j) { const f32x4 gp = *(const f32x4*)(R.gpre + lane * 4 + 256 * j), sh = *(const f32x4*)(shift + lane * 4 + 256 * j), sc = *(const f32x4*)(scale + lane * 4 + 256 * j);
;                     const f32x4 hv = (v[k][j] * rstd * gp) * (sc + 1.0f) + sh;
;                     u32x2 w; w.x = pk2(hv[0], hv[1]); w.y = pk2(hv[2], hv[3]); *(u32x2*)(hr + lane * 4 + 256 * j) = w; }
	v_pk_add_f32 v[84:85], v[84:85], 1.0 op_sel_hi:[1,0]
	v_pk_add_f32 v[86:87], v[86:87], 1.0 op_sel_hi:[1,0]
	v_pk_fma_f32 v[20:21], v[84:85], v[20:21], v[68:69]
	v_pk_fma_f32 v[22:23], v[86:87], v[22:23], v[70:71]
	v_cvt_pk_bf16_f32 v20, v20, v21
	v_cvt_pk_bf16_f32 v21, v22, v23
	global_store_dwordx2 v[252:253], v[20:21], off offset:512
	v_pk_mul_f32 v[24:25], v[24:25], v[164:165] op_sel_hi:[1,0]
	v_pk_mul_f32 v[26:27], v[26:27], v[164:165] op_sel_hi:[1,0]
	v_pk_mul_f32 v[24:25], v[242:243], v[24:25]
	v_pk_mul_f32 v[26:27], v[244:245], v[26:27]
	s_waitcnt vmcnt(8)
	v_pk_add_f32 v[88:89], v[88:89], 1.0 op_sel_hi:[1,0]
	v_pk_add_f32 v[90:91], v[90:91], 1.0 op_sel_hi:[1,0]
	v_pk_fma_f32 v[24:25], v[88:89], v[24:25], v[72:73]
	v_pk_fma_f32 v[26:27], v[90:91], v[26:27], v[74:75]
	v_cvt_pk_bf16_f32 v24, v24, v25
	v_cvt_pk_bf16_f32 v25, v26, v27
	global_store_dwordx2 v[252:253], v[24:25], off offset:1024
	v_pk_mul_f32 v[28:29], v[28:29], v[164:165] op_sel_hi:[1,0]
	v_pk_mul_f32 v[30:31], v[30:31], v[164:165] op_sel_hi:[1,0]
	v_pk_mul_f32 v[28:29], v[246:247], v[28:29]
	v_pk_mul_f32 v[30:31], v[248:249], v[30:31]
	s_waitcnt vmcnt(7)
	v_pk_add_f32 v[92:93], v[92:93], 1.0 op_sel_hi:[1,0]
	v_pk_add_f32 v[94:95], v[94:95], 1.0 op_sel_hi:[1,0]
	v_pk_fma_f32 v[28:29], v[92:93], v[28:29], v[76:77]
	v_pk_fma_f32 v[30:31], v[94:95], v[30:31], v[78:79]
	v_cvt_pk_bf16_f32 v28, v28, v29
	v_cvt_pk_bf16_f32 v29, v30, v31
	global_store_dwordx2 v[252:253], v[28:29], off offset:1536
	s_branch .LBB0_148
.Lr3_slow_same:
	s_add_i32 s72, s7, 0xffffff00
	s_cmp_lg_u64 s[50:51], 0
	s_cselect_b32 s27, s22, s49
	s_cselect_b32 s32, s23, s55
	s_cselect_b32 s37, 24, 20
	s_cselect_b32 s72, s72, s7
	s_cselect_b32 s85, s6, 8
	s_mov_b32 s40, s6
	s_mov_b32 s41, 0
	s_lshl_b64 s[40:41], s[40:41], s37
	s_add_u32 s40, s27, s40
	s_addc_u32 s41, s32, s41
	s_lshl_b32 s72, s72, 12
	s_add_u32 s40, s40, s72
	s_addc_u32 s41, s41, 0
	s_add_i32 s27, s85, s3
	s_mul_hi_i32 s32, s27, 0x6000
	s_mulk_i32 s27, 0x6000
	s_add_u32 s66, s34, s27
	s_addc_u32 s67, s35, s32
	s_add_u32 s66, s66, 0x5000
	s_addc_u32 s67, s67, 0
	s_add_i32 s27, s85, s13
	s_mul_hi_i32 s32, s27, 0x6000
	s_mulk_i32 s27, 0x6000
	s_add_u32 s38, s34, s27
	s_addc_u32 s39, s35, s32
	s_add_u32 s46, s38, 0x1000
	s_addc_u32 s47, s39, 0
	global_load_dwordx4 v[12:15], v160, s[40:41] nt
	global_load_dwordx4 v[8:11], v160, s[40:41] offset:1024 nt
	global_load_dwordx4 v[4:7], v160, s[40:41] offset:2048 nt
	global_load_dwordx4 v[0:3], v160, s[40:41] offset:3072 nt
	global_load_dwordx2 v[54:55], v[46:47], off offset:-1536 nt
	global_load_dwordx2 v[52:53], v[46:47], off offset:-1024 nt
	global_load_dwordx2 v[50:51], v[46:47], off offset:-512 nt
	global_load_dwordx2 v[48:49], v[46:47], off nt
	global_load_dwordx4 v[64:67], v160, s[66:67]
	global_load_dwordx4 v[68:71], v160, s[66:67] offset:1024
	global_load_dwordx4 v[72:75], v160, s[66:67] offset:2048
	global_load_dwordx4 v[76:79], v160, s[66:67] offset:3072
	s_mov_b32 s6, s8
	s_ashr_i32 s7, s8, 31
	s_lshl_b64 s[6:7], s[6:7], 11
	v_lshl_add_u64 v[250:251], v[38:39], 0, s[6:7]
	v_lshl_add_u64 v[252:253], v[40:41], 0, s[6:7]
	s_mov_b64 s[6:7], s[52:53]
	s_add_i32 s72, s25, 0xffffff00
	s_cmp_lg_u64 s[6:7], 0
	s_cselect_b32 s27, s22, s49
	s_cselect_b32 s32, s23, s55
	s_cselect_b32 s37, 24, 20
	s_cselect_b32 s72, s72, s25
	s_cselect_b32 s85, s9, 8
	s_mov_b32 s64, s9
	s_mov_b32 s65, 0
	s_lshl_b64 s[64:65], s[64:65], s37
	s_add_u32 s64, s27, s64
	s_addc_u32 s65, s32, s65
	s_lshl_b32 s72, s72, 12
	s_add_u32 s64, s64, s72
	s_addc_u32 s65, s65, 0
	s_add_i32 s27, s85, s3
	s_mul_hi_i32 s32, s27, 0x6000
	s_mulk_i32 s27, 0x6000
	s_add_u32 s10, s34, s27
	s_addc_u32 s11, s35, s32
	s_add_u32 s10, s10, 0x5000
	s_addc_u32 s11, s11, 0
	s_add_i32 s27, s85, s13
	s_mul_hi_i32 s32, s27, 0x6000
	s_mulk_i32 s27, 0x6000
	s_add_u32 s50, s34, s27
	s_addc_u32 s51, s35, s32
	s_add_u32 s52, s50, 0x1000
	s_addc_u32 s53, s51, 0
	global_load_dwordx4 v[16:19], v160, s[64:65] nt
	global_load_dwordx4 v[20:23], v160, s[64:65] offset:1024 nt
	global_load_dwordx4 v[24:27], v160, s[64:65] offset:2048 nt
	global_load_dwordx4 v[28:31], v160, s[64:65] offset:3072 nt
	global_load_dwordx2 v[62:63], v[250:251], off nt
	global_load_dwordx2 v[60:61], v[250:251], off offset:512 nt
	global_load_dwordx2 v[58:59], v[250:251], off offset:1024 nt
	global_load_dwordx2 v[56:57], v[250:251], off offset:1536 nt
	global_load_dwordx4 v[80:83], v160, s[38:39]
	global_load_dwordx4 v[84:87], v160, s[38:39] offset:1024
	global_load_dwordx4 v[88:91], v160, s[38:39] offset:2048
	global_load_dwordx4 v[92:95], v160, s[38:39] offset:3072
	global_load_dwordx4 v[172:175], v160, s[46:47]
	global_load_dwordx4 v[176:179], v160, s[46:47] offset:1024
	global_load_dwordx4 v[180:183], v160, s[46:47] offset:2048
	global_load_dwordx4 v[184:187], v160, s[46:47] offset:3072
	s_waitcnt vmcnt(20)
; __device__ __forceinline__ unsigned pk2(float lo, float hi) { return pg8::cvt_pk_bf16(lo, hi); }
; __device__ __forceinline__ float bflo(unsigned w) { return __uint_as_float(w << 16); }
; __device__ __forceinline__ float bfhi(unsigned w) { return __uint_as_float(w & 0xffff0000u); }
; __device__ __forceinline__ void row_pass(const RowPass& R, int gw, int ngw, int lane) {
;     ...
;             if (R.update) {
;                 f32x4 y[4]; float ss = 0.f;
; #pragma unroll
;                 for (int j = 0; j < 4; ++j) { const u32x2 w = yw[k][j]; y[j] = (f32x4){bflo(w.x), bfhi(w.x), bflo(w.y), bfhi(w.y)};
;                     ss += (y[j][0] * y[j][0] + y[j][1] * y[j][1]) + (y[j][2] * y[j][2] + y[j][3] * y[j][3]); }
;                 const float rstd = __builtin_amdgcn_rsqf(wave_sum(ss) * (1.0f / DM) + EPS);
;                 const float* gate = R.mod + ((size_t)(R.lg * 9 + bb) * NMOD + R.gi) * DM;
; #pragma unroll
;                 for (int j = 0; j < 4; ++j) { const f32x4 g = *(const f32x4*)(gate + lane * 4 + 256 * j), gp = *(const f32x4*)(R.gpost + lane * 4 + 256 * j);
;                     v[k][j] = v[k][j] + g * (y[j] * rstd * gp); }
;             }
;             if (R.init || R.update) {
; #pragma unroll
;                 for (int j = 0; j < 4; ++j) __builtin_nontemporal_store(v[k][j], (f32x4*)(xrow[k] + lane * 4 + 256 * j));
;             }
;             if (R.norm_out) {
;                 float ss = 0.f;
; #pragma unroll
;                 for (int j = 0; j < 4; ++j) ss += (v[k][j][0] * v[k][j][0] + v[k][j][1] * v[k][j][1]) + (v[k][j][2] * v[k][j][2] + v[k][j][3] * v[k][j][3]);
;                 const float rstd = __builtin_amdgcn_rsqf(wave_sum(ss) * (1.0f / DM) + EPS);
;                 const float* shift = R.mod + ((size_t)(R.ln * 9 + bb) * NMOD + R.si) * DM; const float* scale = shift + DM;
;                 bf16* hr = R.H + (size_t)row * DM;
; #pragma unroll
;                 for (int j = 0; j < 4; ++j) { const f32x4 gp = *(const f32x4*)(R.gpre + lane * 4 + 256 * j), sh = *(const f32x4*)(shift + lane * 4 + 256 * j), sc = *(const f32x4*)(scale + lane * 4 + 256 * j);
;                     const f32x4 hv = (v[k][j] * rstd * gp) * (sc + 1.0f) + sh;
;                     u32x2 w; w.x = pk2(hv[0], hv[1]); w.y = pk2(hv[2], hv[3]); *(u32x2*)(hr + lane * 4 + 256 * j) = w; }
	v_lshlrev_b32_e32 v32, 16, v54
	v_and_b32_e32 v33, 0xffff0000, v54
	v_lshlrev_b32_e32 v34, 16, v55
	v_and_b32_e32 v35, 0xffff0000, v55
	v_pk_mul_f32 v[166:167], v[32:33], v[32:33]
	v_pk_mul_f32 v[168:169], v[34:35], v[34:35]
	v_lshlrev_b32_e32 v32, 16, v52
	v_and_b32_e32 v33, 0xffff0000, v52
	v_lshlrev_b32_e32 v34, 16, v53
	v_and_b32_e32 v35, 0xffff0000, v53
	v_pk_fma_f32 v[166:167], v[32:33], v[32:33], v[166:167]
	v_pk_fma_f32 v[168:169], v[34:35], v[34:35], v[168:169]
	v_lshlrev_b32_e32 v32, 16, v50
	v_and_b32_e32 v33, 0xffff0000, v50
	v_lshlrev_b32_e32 v34, 16, v51
	v_and_b32_e32 v35, 0xffff0000, v51
	v_pk_fma_f32 v[166:167], v[32:33], v[32:33], v[166:167]
	v_pk_fma_f32 v[168:169], v[34:35], v[34:35], v[168:169]
	v_lshlrev_b32_e32 v32, 16, v48
	v_and_b32_e32 v33, 0xffff0000, v48
	v_lshlrev_b32_e32 v34, 16, v49
	v_and_b32_e32 v35, 0xffff0000, v49
	v_pk_fma_f32 v[166:167], v[32:33], v[32:33], v[166:167]
	v_pk_fma_f32 v[168:169], v[34:35], v[34:35], v[168:169]
	v_pk_add_f32 v[166:167], v[166:167], v[168:169]
	s_nop 0
	v_add_f32_e32 v164, v166, v167
	v_mov_b32_e32 v165, v164
	s_nop 1
	v_permlane32_swap_b32_e32 v165, v164
	v_add_f32_e32 v164, v164, v165
	v_mov_b32_e32 v165, v164
	s_nop 1
	v_permlane16_swap_b32_e32 v165, v164
	v_add_f32_e32 v164, v164, v165
	s_nop 1
	v_add_f32_dpp v164, v164, v164 row_ror:8 row_mask:0xf bank_mask:0xf
	s_nop 1
	v_add_f32_dpp v164, v164, v164 row_ror:4 row_mask:0xf bank_mask:0xf
	s_nop 1
	v_add_f32_dpp v164, v164, v164 row_ror:2 row_mask:0xf bank_mask:0xf
	s_nop 1
	v_add_f32_dpp v164, v164, v164 row_ror:1 row_mask:0xf bank_mask:0xf
	s_nop 0
	v_fmamk_f32 v164, v164, 0x3a800000, v200
	v_rsq_f32_e32 v164, v164
	v_lshlrev_b32_e32 v32, 16, v54
	v_and_b32_e32 v33, 0xffff0000, v54
	v_lshlrev_b32_e32 v34, 16, v55
	v_and_b32_e32 v35, 0xffff0000, v55
	v_pk_mul_f32 v[32:33], v[32:33], v[164:165] op_sel_hi:[1,0]
	v_pk_mul_f32 v[34:35], v[34:35], v[164:165] op_sel_hi:[1,0]
	v_pk_mul_f32 v[32:33], v[218:219], v[32:33]
	v_pk_mul_f32 v[34:35], v[220:221], v[34:35]
	s_waitcnt vmcnt(19)
	v_pk_fma_f32 v[12:13], v[64:65], v[32:33], v[12:13]
	v_pk_fma_f32 v[14:15], v[66:67], v[34:35], v[14:15]
	global_store_dwordx4 v160, v[12:15], s[40:41] nt
	v_lshlrev_b32_e32 v32, 16, v52
	v_and_b32_e32 v33, 0xffff0000, v52
	v_lshlrev_b32_e32 v34, 16, v53
	v_and_b32_e32 v35, 0xffff0000, v53
	v_pk_mul_f32 v[32:33], v[32:33], v[164:165] op_sel_hi:[1,0]
	v_pk_mul_f32 v[34:35], v[34:35], v[164:165] op_sel_hi:[1,0]
	v_pk_mul_f32 v[32:33], v[222:223], v[32:33]
	v_pk_mul_f32 v[34:35], v[224:225], v[34:35]
	s_waitcnt vmcnt(19)
	v_pk_fma_f32 v[8:9], v[68:69], v[32:33], v[8:9]
	v_pk_fma_f32 v[10:11], v[70:71], v[34:35], v[10:11]
	global_store_dwordx4 v160, v[8:11], s[40:41] offset:1024 nt
	v_lshlrev_b32_e32 v32, 16, v50
	v_and_b32_e32 v33, 0xffff0000, v50
	v_lshlrev_b32_e32 v34, 16, v51
	v_and_b32_e32 v35, 0xffff0000, v51
	v_pk_mul_f32 v[32:33], v[32:33], v[164:165] op_sel_hi:[1,0]
	v_pk_mul_f32 v[34:35], v[34:35], v[164:165] op_sel_hi:[1,0]
	v_pk_mul_f32 v[32:33], v[226:227], v[32:33]
	v_pk_mul_f32 v[34:35], v[228:229], v[34:35]
	s_waitcnt vmcnt(19)
	v_pk_fma_f32 v[4:5], v[72:73], v[32:33], v[4:5]
	v_pk_fma_f32 v[6:7], v[74:75], v[34:35], v[6:7]
	global_store_dwordx4 v160, v[4:7], s[40:41] offset:2048 nt
	v_lshlrev_b32_e32 v32, 16, v48
	v_and_b32_e32 v33, 0xffff0000, v48
	v_lshlrev_b32_e32 v34, 16, v49
	v_and_b32_e32 v35, 0xffff0000, v49
	v_pk_mul_f32 v[32:33], v[32:33], v[164:165] op_sel_hi:[1,0]
	v_pk_mul_f32 v[34:35], v[34:35], v[164:165] op_sel_hi:[1,0]
	v_pk_mul_f32 v[32:33], v[230:231], v[32:33]
	v_pk_mul_f32 v[34:35], v[232:233], v[34:35]
	s_waitcnt vmcnt(19)
	v_pk_fma_f32 v[0:1], v[76:77], v[32:33], v[0:1]
	v_pk_fma_f32 v[2:3], v[78:79], v[34:35], v[2:3]
	global_store_dwordx4 v160, v[0:3], s[40:41] offset:3072 nt
	v_add_co_u32_e32 v250, vcc, 0xfbc00000, v46
	v_addc_co_u32_e32 v251, vcc, -1, v47, vcc
	v_pk_mul_f32 v[166:167], v[12:13], v[12:13]
	v_pk_mul_f32 v[168:169], v[14:15], v[14:15]
	v_pk_fma_f32 v[166:167], v[8:9], v[8:9], v[166:167]
	v_pk_fma_f32 v[168:169], v[10:11], v[10:11], v[168:169]
	v_pk_fma_f32 v[166:167], v[4:5], v[4:5], v[166:167]
	v_pk_fma_f32 v[168:169], v[6:7], v[6:7], v[168:169]
	v_pk_fma_f32 v[166:167], v[0:1], v[0:1], v[166:167]
	v_pk_fma_f32 v[168:169], v[2:3], v[2:3], v[168:169]
	v_pk_add_f32 v[166:167], v[166:167], v[168:169]
	s_nop 0
	v_add_f32_e32 v164, v166, v167
	v_mov_b32_e32 v165, v164
	s_nop 1
	v_permlane32_swap_b32_e32 v165, v164
	v_add_f32_e32 v164, v164, v165
	v_mov_b32_e32 v165, v164
	s_nop 1
	v_permlane16_swap_b32_e32 v165, v164
	v_add_f32_e32 v164, v164, v165
	s_nop 1
	v_add_f32_dpp v164, v164, v164 row_ror:8 row_mask:0xf bank_mask:0xf
	s_nop 1
	v_add_f32_dpp v164, v164, v164 row_ror:4 row_mask:0xf bank_mask:0xf
	s_nop 1
	v_add_f32_dpp v164, v164, v164 row_ror:2 row_mask:0xf bank_mask:0xf
	s_nop 1
	v_add_f32_dpp v164, v164, v164 row_ror:1 row_mask:0xf bank_mask:0xf
	s_nop 0
	v_fmamk_f32 v164, v164, 0x3a800000, v200
	v_rsq_f32_e32 v164, v164
	s_nop 0
	v_pk_mul_f32 v[12:13], v[12:13], v[164:165] op_sel_hi:[1,0]
	v_pk_mul_f32 v[14:15], v[14:15], v[164:165] op_sel_hi:[1,0]
	v_pk_mul_f32 v[12:13], v[234:235], v[12:13]
	v_pk_mul_f32 v[14:15], v[236:237], v[14:15]
	s_waitcnt vmcnt(7)
	v_pk_add_f32 v[172:173], v[172:173], 1.0 op_sel_hi:[1,0]
	v_pk_add_f32 v[174:175], v[174:175], 1.0 op_sel_hi:[1,0]
	v_pk_fma_f32 v[12:13], v[172:173], v[12:13], v[80:81]
	v_pk_fma_f32 v[14:15], v[174:175], v[14:15], v[82:83]
	v_cvt_pk_bf16_f32 v12, v12, v13
	v_cvt_pk_bf16_f32 v13, v14, v15
	global_store_dwordx2 v[250:251], v[12:13], off offset:-1536
	v_pk_mul_f32 v[8:9], v[8:9], v[164:165] op_sel_hi:[1,0]
	v_pk_mul_f32 v[10:11], v[10:11], v[164:165] op_sel_hi:[1,0]
	v_pk_mul_f32 v[8:9], v[238:239], v[8:9]
	v_pk_mul_f32 v[10:11], v[240:241], v[10:11]
	s_waitcnt vmcnt(7)
; __device__ __forceinline__ unsigned pk2(float lo, float hi) { return pg8::cvt_pk_bf16(lo, hi); }
; __device__ __forceinline__ float bflo(unsigned w) { return __uint_as_float(w << 16); }
; __device__ __forceinline__ float bfhi(unsigned w) { return __uint_as_float(w & 0xffff0000u); }
; __device__ __forceinline__ void row_pass(const RowPass& R, int gw, int ngw, int lane) {
;     ...
;             if (R.update) {
;                 f32x4 y[4]; float ss = 0.f;
; #pragma unroll
;                 for (int j = 0; j < 4; ++j) { const u32x2 w = yw[k][j]; y[j] = (f32x4){bflo(w.x), bfhi(w.x), bflo(w.y), bfhi(w.y)};
;                     ss += (y[j][0] * y[j][0] + y[j][1] * y[j][1]) + (y[j][2] * y[j][2] + y[j][3] * y[j][3]); }
;                 const float rstd = __builtin_amdgcn_rsqf(wave_sum(ss) * (1.0f / DM) + EPS);
;                 const float* gate = R.mod + ((size_t)(R.lg * 9 + bb) * NMOD + R.gi) * DM;
; #pragma unroll
;                 for (int j = 0; j < 4; ++j) { const f32x4 g = *(const f32x4*)(gate + lane * 4 + 256 * j), gp = *(const f32x4*)(R.gpost + lane * 4 + 256 * j);
;                     v[k][j] = v[k][j] + g * (y[j] * rstd * gp); }
;             }
;     ...
;             if (R.norm_out) {
;                 float ss = 0.f;
; #pragma unroll
;                 for (int j = 0; j < 4; ++j) ss += (v[k][j][0] * v[k][j][0] + v[k][j][1] * v[k][j][1]) + (v[k][j][2] * v[k][j][2] + v[k][j][3] * v[k][j][3]);
;                 const float rstd = __builtin_amdgcn_rsqf(wave_sum(ss) * (1.0f / DM) + EPS);
;                 const float* shift = R.mod + ((size_t)(R.ln * 9 + bb) * NMOD + R.si) * DM; const float* scale = shift + DM;
;                 bf16* hr = R.H + (size_t)row * DM;
; #pragma unroll
;                 for (int j = 0; j < 4; ++j) { const f32x4 gp = *(const f32x4*)(R.gpre + lane * 4 + 256 * j), sh = *(const f32x4*)(shift + lane * 4 + 256 * j), sc = *(const f32x4*)(scale + lane * 4 + 256 * j);
;                     const f32x4 hv = (v[k][j] * rstd * gp) * (sc + 1.0f) + sh;
;                     u32x2 w; w.x = pk2(hv[0], hv[1]); w.y = pk2(hv[2], hv[3]); *(u32x2*)(hr + lane * 4 + 256 * j) = w; }
	v_pk_add_f32 v[176:177], v[176:177], 1.0 op_sel_hi:[1,0]
	v_pk_add_f32 v[178:179], v[178:179], 1.0 op_sel_hi:[1,0]
	v_pk_fma_f32 v[8:9], v[176:177], v[8:9], v[84:85]
	v_pk_fma_f32 v[10:11], v[178:179], v[10:11], v[86:87]
	v_cvt_pk_bf16_f32 v8, v8, v9
	v_cvt_pk_bf16_f32 v9, v10, v11
	global_store_dwordx2 v[250:251], v[8:9], off offset:-1024
	v_pk_mul_f32 v[4:5], v[4:5], v[164:165] op_sel_hi:[1,0]
	v_pk_mul_f32 v[6:7], v[6:7], v[164:165] op_sel_hi:[1,0]
	v_pk_mul_f32 v[4:5], v[242:243], v[4:5]
	v_pk_mul_f32 v[6:7], v[244:245], v[6:7]
	s_waitcnt vmcnt(7)
	v_pk_add_f32 v[180:181], v[180:181], 1.0 op_sel_hi:[1,0]
	v_pk_add_f32 v[182:183], v[182:183], 1.0 op_sel_hi:[1,0]
	v_pk_fma_f32 v[4:5], v[180:181], v[4:5], v[88:89]
	v_pk_fma_f32 v[6:7], v[182:183], v[6:7], v[90:91]
	v_cvt_pk_bf16_f32 v4, v4, v5
	v_cvt_pk_bf16_f32 v5, v6, v7
	global_store_dwordx2 v[250:251], v[4:5], off offset:-512
	v_pk_mul_f32 v[0:1], v[0:1], v[164:165] op_sel_hi:[1,0]
	v_pk_mul_f32 v[2:3], v[2:3], v[164:165] op_sel_hi:[1,0]
	v_pk_mul_f32 v[0:1], v[246:247], v[0:1]
	v_pk_mul_f32 v[2:3], v[248:249], v[2:3]
	s_waitcnt vmcnt(7)
	v_pk_add_f32 v[184:185], v[184:185], 1.0 op_sel_hi:[1,0]
	v_pk_add_f32 v[186:187], v[186:187], 1.0 op_sel_hi:[1,0]
	v_pk_fma_f32 v[0:1], v[184:185], v[0:1], v[92:93]
	v_pk_fma_f32 v[2:3], v[186:187], v[2:3], v[94:95]
	v_cvt_pk_bf16_f32 v0, v0, v1
	v_cvt_pk_bf16_f32 v1, v2, v3
	global_store_dwordx2 v[250:251], v[0:1], off
	s_waitcnt vmcnt(16)
	v_lshlrev_b32_e32 v32, 16, v62
	v_and_b32_e32 v33, 0xffff0000, v62
	v_lshlrev_b32_e32 v34, 16, v63
	v_and_b32_e32 v35, 0xffff0000, v63
	v_pk_mul_f32 v[166:167], v[32:33], v[32:33]
	v_pk_mul_f32 v[168:169], v[34:35], v[34:35]
	v_lshlrev_b32_e32 v32, 16, v60
	v_and_b32_e32 v33, 0xffff0000, v60
	v_lshlrev_b32_e32 v34, 16, v61
	v_and_b32_e32 v35, 0xffff0000, v61
	v_pk_fma_f32 v[166:167], v[32:33], v[32:33], v[166:167]
	v_pk_fma_f32 v[168:169], v[34:35], v[34:35], v[168:169]
	v_lshlrev_b32_e32 v32, 16, v58
	v_and_b32_e32 v33, 0xffff0000, v58
	v_lshlrev_b32_e32 v34, 16, v59
	v_and_b32_e32 v35, 0xffff0000, v59
	v_pk_fma_f32 v[166:167], v[32:33], v[32:33], v[166:167]
	v_pk_fma_f32 v[168:169], v[34:35], v[34:35], v[168:169]
	v_lshlrev_b32_e32 v32, 16, v56
	v_and_b32_e32 v33, 0xffff0000, v56
	v_lshlrev_b32_e32 v34, 16, v57
	v_and_b32_e32 v35, 0xffff0000, v57
	v_pk_fma_f32 v[166:167], v[32:33], v[32:33], v[166:167]
	v_pk_fma_f32 v[168:169], v[34:35], v[34:35], v[168:169]
	v_pk_add_f32 v[166:167], v[166:167], v[168:169]
	s_nop 0
	v_add_f32_e32 v164, v166, v167
	v_mov_b32_e32 v165, v164
	s_nop 1
	v_permlane32_swap_b32_e32 v165, v164
	v_add_f32_e32 v164, v164, v165
	v_mov_b32_e32 v165, v164
	s_nop 1
	v_permlane16_swap_b32_e32 v165, v164
	v_add_f32_e32 v164, v164, v165
	s_nop 1
	v_add_f32_dpp v164, v164, v164 row_ror:8 row_mask:0xf bank_mask:0xf
	s_nop 1
	v_add_f32_dpp v164, v164, v164 row_ror:4 row_mask:0xf bank_mask:0xf
	s_nop 1
	v_add_f32_dpp v164, v164, v164 row_ror:2 row_mask:0xf bank_mask:0xf
	s_nop 1
	v_add_f32_dpp v164, v164, v164 row_ror:1 row_mask:0xf bank_mask:0xf
	s_nop 0
	v_fmamk_f32 v164, v164, 0x3a800000, v200
	v_rsq_f32_e32 v164, v164
	v_lshlrev_b32_e32 v32, 16, v62
	v_and_b32_e32 v33, 0xffff0000, v62
	v_lshlrev_b32_e32 v34, 16, v63
	v_and_b32_e32 v35, 0xffff0000, v63
	v_pk_mul_f32 v[32:33], v[32:33], v[164:165] op_sel_hi:[1,0]
	v_pk_mul_f32 v[34:35], v[34:35], v[164:165] op_sel_hi:[1,0]
	v_pk_mul_f32 v[32:33], v[218:219], v[32:33]
	v_pk_mul_f32 v[34:35], v[220:221], v[34:35]
	s_waitcnt vmcnt(27)
	v_pk_fma_f32 v[16:17], v[64:65], v[32:33], v[16:17]
	v_pk_fma_f32 v[18:19], v[66:67], v[34:35], v[18:19]
	global_store_dwordx4 v160, v[16:19], s[64:65] nt
	v_lshlrev_b32_e32 v32, 16, v60
	v_and_b32_e32 v33, 0xffff0000, v60
	v_lshlrev_b32_e32 v34, 16, v61
	v_and_b32_e32 v35, 0xffff0000, v61
	v_pk_mul_f32 v[32:33], v[32:33], v[164:165] op_sel_hi:[1,0]
	v_pk_mul_f32 v[34:35], v[34:35], v[164:165] op_sel_hi:[1,0]
	v_pk_mul_f32 v[32:33], v[222:223], v[32:33]
	v_pk_mul_f32 v[34:35], v[224:225], v[34:35]
	s_waitcnt vmcnt(27)
; __device__ __forceinline__ unsigned pk2(float lo, float hi) { return pg8::cvt_pk_bf16(lo, hi); }
;     __device__ __forceinline__ void init(int N, int G, int c, int latent_only) { lat = latent_only; b.init(latent_only ? NB * SEQ : M, N, G, c); }
;     __device__ __forceinline__ void init(int c_, unsigned* cnt_) { lat.init(NB * SEQ, FF2, 1, 0); c = c_; cnt = cnt_; }
; __device__ __forceinline__ void row_pass(const RowPass& R, int gw, int ngw, int lane) {
;     ...
;                 for (int j = 0; j < 4; ++j) { const f32x4 g = *(const f32x4*)(gate + lane * 4 + 256 * j), gp = *(const f32x4*)(R.gpost + lane * 4 + 256 * j);
;                     v[k][j] = v[k][j] + g * (y[j] * rstd * gp); }
;             }
;             if (R.init || R.update) {
; #pragma unroll
;                 for (int j = 0; j < 4; ++j) __builtin_nontemporal_store(v[k][j], (f32x4*)(xrow[k] + lane * 4 + 256 * j));
;             }
;             if (R.norm_out) {
;                 float ss = 0.f;
; #pragma unroll
;                 for (int j = 0; j < 4; ++j) ss += (v[k][j][0] * v[k][j][0] + v[k][j][1] * v[k][j][1]) + (v[k][j][2] * v[k][j][2] + v[k][j][3] * v[k][j][3]);
;                 const float rstd = __builtin_amdgcn_rsqf(wave_sum(ss) * (1.0f / DM) + EPS);
;                 const float* shift = R.mod + ((size_t)(R.ln * 9 + bb) * NMOD + R.si) * DM; const float* scale = shift + DM;
;                 bf16* hr = R.H + (size_t)row * DM;
; #pragma unroll
;                 for (int j = 0; j < 4; ++j) { const f32x4 gp = *(const f32x4*)(R.gpre + lane * 4 + 256 * j), sh = *(const f32x4*)(shift + lane * 4 + 256 * j), sc = *(const f32x4*)(scale + lane * 4 + 256 * j);
;                     const f32x4 hv = (v[k][j] * rstd * gp) * (sc + 1.0f) + sh;
;                     u32x2 w; w.x = pk2(hv[0], hv[1]); w.y = pk2(hv[2], hv[3]); *(u32x2*)(hr + lane * 4 + 256 * j) = w; }
	v_pk_fma_f32 v[20:21], v[68:69], v[32:33], v[20:21]
	v_pk_fma_f32 v[22:23], v[70:71], v[34:35], v[22:23]
	global_store_dwordx4 v160, v[20:23], s[64:65] offset:1024 nt
	v_lshlrev_b32_e32 v32, 16, v58
	v_and_b32_e32 v33, 0xffff0000, v58
	v_lshlrev_b32_e32 v34, 16, v59
	v_and_b32_e32 v35, 0xffff0000, v59
	v_pk_mul_f32 v[32:33], v[32:33], v[164:165] op_sel_hi:[1,0]
	v_pk_mul_f32 v[34:35], v[34:35], v[164:165] op_sel_hi:[1,0]
	v_pk_mul_f32 v[32:33], v[226:227], v[32:33]
	v_pk_mul_f32 v[34:35], v[228:229], v[34:35]
	s_waitcnt vmcnt(27)
	v_pk_fma_f32 v[24:25], v[72:73], v[32:33], v[24:25]
	v_pk_fma_f32 v[26:27], v[74:75], v[34:35], v[26:27]
	global_store_dwordx4 v160, v[24:27], s[64:65] offset:2048 nt
	v_lshlrev_b32_e32 v32, 16, v56
	v_and_b32_e32 v33, 0xffff0000, v56
	v_lshlrev_b32_e32 v34, 16, v57
	v_and_b32_e32 v35, 0xffff0000, v57
	v_pk_mul_f32 v[32:33], v[32:33], v[164:165] op_sel_hi:[1,0]
	v_pk_mul_f32 v[34:35], v[34:35], v[164:165] op_sel_hi:[1,0]
	v_pk_mul_f32 v[32:33], v[230:231], v[32:33]
	v_pk_mul_f32 v[34:35], v[232:233], v[34:35]
	s_waitcnt vmcnt(27)
	v_pk_fma_f32 v[28:29], v[76:77], v[32:33], v[28:29]
	v_pk_fma_f32 v[30:31], v[78:79], v[34:35], v[30:31]
	global_store_dwordx4 v160, v[28:31], s[64:65] offset:3072 nt
	v_pk_mul_f32 v[166:167], v[16:17], v[16:17]
	v_pk_mul_f32 v[168:169], v[18:19], v[18:19]
	v_pk_fma_f32 v[166:167], v[20:21], v[20:21], v[166:167]
	v_pk_fma_f32 v[168:169], v[22:23], v[22:23], v[168:169]
	v_pk_fma_f32 v[166:167], v[24:25], v[24:25], v[166:167]
	v_pk_fma_f32 v[168:169], v[26:27], v[26:27], v[168:169]
	v_pk_fma_f32 v[166:167], v[28:29], v[28:29], v[166:167]
	v_pk_fma_f32 v[168:169], v[30:31], v[30:31], v[168:169]
	v_pk_add_f32 v[166:167], v[166:167], v[168:169]
	s_nop 0
	v_add_f32_e32 v164, v166, v167
	v_mov_b32_e32 v165, v164
	s_nop 1
	v_permlane32_swap_b32_e32 v165, v164
	v_add_f32_e32 v164, v164, v165
	v_mov_b32_e32 v165, v164
	s_nop 1
	v_permlane16_swap_b32_e32 v165, v164
	v_add_f32_e32 v164, v164, v165
	s_nop 1
	v_add_f32_dpp v164, v164, v164 row_ror:8 row_mask:0xf bank_mask:0xf
	s_nop 1
	v_add_f32_dpp v164, v164, v164 row_ror:4 row_mask:0xf bank_mask:0xf
	s_nop 1
	v_add_f32_dpp v164, v164, v164 row_ror:2 row_mask:0xf bank_mask:0xf
	s_nop 1
	v_add_f32_dpp v164, v164, v164 row_ror:1 row_mask:0xf bank_mask:0xf
	s_nop 0
	v_fmamk_f32 v164, v164, 0x3a800000, v200
	v_rsq_f32_e32 v164, v164
	s_nop 0
	v_pk_mul_f32 v[16:17], v[16:17], v[164:165] op_sel_hi:[1,0]
	v_pk_mul_f32 v[18:19], v[18:19], v[164:165] op_sel_hi:[1,0]
	v_pk_mul_f32 v[16:17], v[234:235], v[16:17]
	v_pk_mul_f32 v[18:19], v[236:237], v[18:19]
	s_waitcnt vmcnt(15)
	v_pk_fma_f32 v[16:17], v[172:173], v[16:17], v[80:81]
	v_pk_fma_f32 v[18:19], v[174:175], v[18:19], v[82:83]
	v_cvt_pk_bf16_f32 v16, v16, v17
	v_cvt_pk_bf16_f32 v17, v18, v19
	global_store_dwordx2 v[252:253], v[16:17], off
	v_pk_mul_f32 v[20:21], v[20:21], v[164:165] op_sel_hi:[1,0]
	v_pk_mul_f32 v[22:23], v[22:23], v[164:165] op_sel_hi:[1,0]
	v_pk_mul_f32 v[20:21], v[238:239], v[20:21]
	v_pk_mul_f32 v[22:23], v[240:241], v[22:23]
	s_waitcnt vmcnt(15)
	v_pk_fma_f32 v[20:21], v[176:177], v[20:21], v[84:85]
	v_pk_fma_f32 v[22:23], v[178:179], v[22:23], v[86:87]
	v_cvt_pk_bf16_f32 v20, v20, v21
	v_cvt_pk_bf16_f32 v21, v22, v23
	global_store_dwordx2 v[252:253], v[20:21], off offset:512
	v_pk_mul_f32 v[24:25], v[24:25], v[164:165] op_sel_hi:[1,0]
	v_pk_mul_f32 v[26:27], v[26:27], v[164:165] op_sel_hi:[1,0]
	v_pk_mul_f32 v[24:25], v[242:243], v[24:25]
	v_pk_mul_f32 v[26:27], v[244:245], v[26:27]
	s_waitcnt vmcnt(15)
	v_pk_fma_f32 v[24:25], v[180:181], v[24:25], v[88:89]
	v_pk_fma_f32 v[26:27], v[182:183], v[26:27], v[90:91]
	v_cvt_pk_bf16_f32 v24, v24, v25
	v_cvt_pk_bf16_f32 v25, v26, v27
	global_store_dwordx2 v[252:253], v[24:25], off offset:1024
	v_pk_mul_f32 v[28:29], v[28:29], v[164:165] op_sel_hi:[1,0]
	v_pk_mul_f32 v[30:31], v[30:31], v[164:165] op_sel_hi:[1,0]
	v_pk_mul_f32 v[28:29], v[246:247], v[28:29]
	v_pk_mul_f32 v[30:31], v[248:249], v[30:31]
	s_waitcnt vmcnt(15)
	v_pk_fma_f32 v[28:29], v[184:185], v[28:29], v[92:93]
	v_pk_fma_f32 v[30:31], v[186:187], v[30:31], v[94:95]
	v_cvt_pk_bf16_f32 v28, v28, v29
	v_cvt_pk_bf16_f32 v29, v30, v31
	global_store_dwordx2 v[252:253], v[28:29], off offset:1536
	s_branch .LBB0_148
